# gslayout_v105 + GDN N records in [w][half][lane] layout (GDN prep producer, prompt scan and sample scan consumers)
# baseline (speedup 1.0000x reference)
.LBB0_512:
	s_or_b64 exec, exec, s[12:13]
	s_waitcnt lgkmcnt(6)
	v_lshlrev_b32_e32 v179, 16, v178
	v_lshlrev_b32_e32 v178, 16, v61
	v_lshlrev_b32_e32 v198, 1, v89
	v_pk_mul_f32 v[60:61], v[48:49], v[178:179]
	v_lshlrev_b32_e32 v179, 16, v177
	v_lshlrev_b32_e32 v178, 16, v153
	v_lshlrev_b32_e32 v153, 16, v176
	v_lshlrev_b32_e32 v176, 16, v103
	v_lshlrev_b32_e32 v103, 16, v104
	v_lshlrev_b32_e32 v102, 16, v102
	v_lshl_or_b32 v89, v109, 5, v198
	v_pk_mul_f32 v[184:185], v[52:53], v[178:179]
	v_pk_mul_f32 v[178:179], v[58:59], v[102:103]
	v_lshlrev_b32_e32 v102, 16, v100
	v_lshlrev_b32_e32 v189, 16, v101
	ds_read_u16 v190, v106 offset:7056
	ds_read_u16 v191, v106 offset:6912
	ds_read_u16 v192, v106 offset:7200
	ds_read_u16 v193, v106 offset:7344
	ds_read_u16 v194, v106 offset:7376
	ds_read_u16 v195, v106 offset:7232
	ds_read_u16 v196, v106 offset:7088
	ds_read_u16 v197, v106 offset:6944
	ds_read_b64 v[100:101], v89 offset:59392
	v_lshlrev_b32_e32 v103, 16, v105
	v_pk_mul_f32 v[186:187], v[56:57], v[102:103]
	v_mov_b32_e32 v102, v28
	v_mov_b32_e32 v103, v28
	v_lshlrev_b32_e32 v177, 16, v107
	v_pk_mul_f32 v[176:177], v[56:57], v[176:177]
	v_cvt_pk_bf16_f32 v105, v178, v179
	v_cvt_pk_bf16_f32 v104, v176, v177
	v_mov_b32_e32 v106, v28
	v_mov_b32_e32 v107, v28
	v_cndmask_b32_e64 v199, v159, v162, s[8:9]
	v_or_b32_e32 v188, v199, v198
	s_waitcnt lgkmcnt(0)
	v_mfma_f32_16x16x32_bf16 v[100:103], v[100:103], v[104:107], 0
	v_mad_u32_u24 v200, v62, s82, v188
	v_lshlrev_b32_e32 v188, 16, v96
	v_cmp_lt_u32_e64 s[8:9], 31, v167
	v_lshlrev_b32_e32 v152, 16, v152
	v_mul_f32_e32 v40, 0x3fb8aa3b, v40
	s_nop 2
	v_cvt_pk_bf16_f32 v56, v100, v101
	v_cvt_pk_bf16_f32 v57, v102, v103
	ds_write_b64 v200, v[56:57]
	ds_read_b64 v[56:57], v89 offset:59392
	v_pk_mul_f32 v[102:103], v[58:59], v[188:189]
	v_mov_b32_e32 v58, v28
	v_mov_b32_e32 v59, v28
	v_cvt_pk_bf16_f32 v100, v186, v187
	v_cvt_pk_bf16_f32 v101, v102, v103
	v_mov_b32_e32 v102, v28
	v_mov_b32_e32 v103, v28
	v_add_u32_e32 v188, v68, v88
	v_or_b32_e32 v88, v199, v68
	s_waitcnt lgkmcnt(0)
	v_mfma_f32_16x16x32_bf16 v[56:59], v[56:59], v[100:103], 0
	v_mad_u32_u24 v189, v62, s82, v88
	ds_read_b128 v[100:103], v189
	v_pk_mul_f32 v[186:187], v[54:55], v[152:153]
	v_lshl_or_b32 v88, v172, 5, v198
	v_lshlrev_b32_e32 v62, 16, v92
	s_nop 2
	v_cvt_pk_bf16_f32 v56, v56, v57
	v_cvt_pk_bf16_f32 v57, v58, v59
	ds_write_b64 v200, v[56:57] offset:2304
	ds_read_b128 v[56:59], v188 offset:48384
	ds_read_b64 v[104:105], v88 offset:59392
	ds_read_b128 v[176:179], v189 offset:2304
	v_lshlrev_b32_e32 v89, 16, v99
	v_mul_f32_e32 v41, 0x3fb8aa3b, v41
	v_mul_f32_e32 v43, 0x3fb8aa3b, v43
	s_waitcnt lgkmcnt(2)
	v_cndmask_b32_e64 v59, v59, 0, s[8:9]
	v_cndmask_b32_e64 v58, v58, 0, s[8:9]
	v_cndmask_b32_e64 v57, v57, 0, s[8:9]
	v_cndmask_b32_e64 v56, v56, 0, s[8:9]
	s_nop 1
	v_mfma_f32_16x16x32_bf16 v[56:59], v[56:59], v[100:103], v[184:187]
	v_lshlrev_b32_e32 v101, 16, v94
	v_lshlrev_b32_e32 v100, 16, v63
	v_pk_mul_f32 v[52:53], v[52:53], v[100:101]
	s_nop 4
	v_cvt_pk_bf16_f32 v56, v56, v57
	v_cvt_pk_bf16_f32 v57, v58, v59
	v_mov_b32_e32 v58, v28
	v_mov_b32_e32 v59, v28
	v_lshlrev_b32_e32 v63, 16, v93
	v_pk_mul_f32 v[54:55], v[54:55], v[62:63]
	s_waitcnt lgkmcnt(1)
	v_mfma_f32_16x16x32_bf16 v[56:59], v[104:107], v[56:59], 0
	v_mov_b32_e32 v102, v28
	v_mov_b32_e32 v103, v28
	v_mov_b32_e32 v94, v28
	s_nop 4
	v_cvt_pk_bf16_f32 v56, v56, v57
	v_cvt_pk_bf16_f32 v57, v58, v59
	ds_write_b64 v200, v[56:57] offset:32
	ds_read_b128 v[56:59], v188 offset:48384
	ds_read_b64 v[100:101], v88 offset:59392
	v_lshlrev_b32_e32 v88, 16, v97
	v_pk_mul_f32 v[62:63], v[50:51], v[88:89]
	v_lshlrev_b32_e32 v88, 16, v95
	s_waitcnt lgkmcnt(1)
	v_cndmask_b32_e64 v59, v59, 0, s[8:9]
	v_cndmask_b32_e64 v58, v58, 0, s[8:9]
	v_cndmask_b32_e64 v57, v57, 0, s[8:9]
	v_cndmask_b32_e64 v56, v56, 0, s[8:9]
	v_mov_b32_e32 v95, v28
	v_lshlrev_b32_e32 v89, 16, v98
	v_mfma_f32_16x16x32_bf16 v[52:55], v[56:59], v[176:179], v[52:55]
	ds_read_b128 v[56:59], v189
	v_pk_mul_f32 v[48:49], v[48:49], v[88:89]
	s_nop 5
	v_cvt_pk_bf16_f32 v52, v52, v53
	v_cvt_pk_bf16_f32 v53, v54, v55
	v_mov_b32_e32 v54, v28
	v_mov_b32_e32 v55, v28
	s_waitcnt lgkmcnt(1)
	s_nop 0
	v_mfma_f32_16x16x32_bf16 v[52:55], v[100:103], v[52:55], 0
	v_lshl_or_b32 v100, v173, 5, v198
	s_nop 6
	v_cvt_pk_bf16_f32 v52, v52, v53
	v_cvt_pk_bf16_f32 v53, v54, v55
	ds_write_b64 v200, v[52:53] offset:2336
	ds_read_b128 v[52:55], v188 offset:50688
	s_waitcnt lgkmcnt(0)
	v_mfma_f32_16x16x32_bf16 v[52:55], v[52:55], v[56:59], v[60:63]
	ds_read_b64 v[92:93], v100 offset:59392
	ds_read_b128 v[96:99], v189 offset:2304
	s_nop 0
	v_lshlrev_b32_e32 v61, 16, v91
	v_lshlrev_b32_e32 v60, 16, v90
	s_nop 2
	v_cvt_pk_bf16_f32 v52, v52, v53
	v_cvt_pk_bf16_f32 v53, v54, v55
	v_mov_b32_e32 v54, v28
	v_mov_b32_e32 v55, v28
	v_pk_mul_f32 v[50:51], v[50:51], v[60:61]
	v_mov_b32_e32 v90, v28
	s_waitcnt lgkmcnt(1)
	v_mfma_f32_16x16x32_bf16 v[52:55], v[92:95], v[52:55], 0
	v_mov_b32_e32 v91, v28
	v_lshlrev_b32_e32 v61, 16, v190
	v_lshlrev_b32_e32 v60, 16, v191
	v_lshlrev_b32_e32 v63, 16, v193
	v_lshlrev_b32_e32 v62, 16, v192
	s_nop 2
	v_cvt_pk_bf16_f32 v52, v52, v53
	v_cvt_pk_bf16_f32 v53, v54, v55
	ds_write_b64 v200, v[52:53] offset:64
	ds_read_b128 v[52:55], v188 offset:50688
	ds_read_b64 v[88:89], v100 offset:59392
	s_waitcnt lgkmcnt(1)
	v_mfma_f32_16x16x32_bf16 v[48:51], v[52:55], v[96:99], v[48:51]
	v_mul_f32_e64 v60, v44, v60
	v_mul_f32_e64 v61, v45, v61
	v_pk_mul_f32 v[62:63], v[46:47], v[62:63]
	v_lshl_or_b32 v92, v174, 5, v198
	s_nop 3
	v_cvt_pk_bf16_f32 v48, v48, v49
	v_cvt_pk_bf16_f32 v49, v50, v51
	v_mov_b32_e32 v50, v28
	v_mov_b32_e32 v51, v28
	s_waitcnt lgkmcnt(0)
	s_nop 0
	v_mfma_f32_16x16x32_bf16 v[48:51], v[88:91], v[48:51], 0
	s_nop 7
	v_cvt_pk_bf16_f32 v48, v48, v49
	v_cvt_pk_bf16_f32 v49, v50, v51
	ds_write_b64 v200, v[48:49] offset:2368
	ds_read_b128 v[48:51], v188 offset:52992
	ds_read_b128 v[52:55], v188 offset:53056
	ds_read_b128 v[88:91], v189 offset:64
	s_waitcnt lgkmcnt(2)
	v_mfma_f32_16x16x32_bf16 v[48:51], v[48:51], v[56:59], v[60:63]
	s_waitcnt lgkmcnt(1)
	v_cndmask_b32_e64 v55, v55, 0, s[8:9]
	v_cndmask_b32_e64 v54, v54, 0, s[8:9]
	v_cndmask_b32_e64 v53, v53, 0, s[8:9]
	v_cndmask_b32_e64 v52, v52, 0, s[8:9]
	v_mov_b32_e32 v58, v28
	v_mov_b32_e32 v59, v28
	s_waitcnt lgkmcnt(0)
	v_mfma_f32_16x16x32_bf16 v[48:51], v[52:55], v[88:91], v[48:51]
	ds_read_b64 v[56:57], v92 offset:59392
	ds_read_b128 v[60:63], v189 offset:2368
	v_lshlrev_b32_e32 v53, 16, v196
	v_lshlrev_b32_e32 v52, 16, v197
	s_nop 3
	v_cvt_pk_bf16_f32 v48, v48, v49
	v_cvt_pk_bf16_f32 v49, v50, v51
	v_mov_b32_e32 v50, v28
	v_mov_b32_e32 v51, v28
	v_pk_mul_f32 v[44:45], v[44:45], v[52:53]
	s_waitcnt lgkmcnt(1)
	v_mfma_f32_16x16x32_bf16 v[48:51], v[56:59], v[48:51], 0
	v_lshlrev_b32_e32 v57, 16, v194
	v_lshlrev_b32_e32 v56, 16, v195
	v_pk_mul_f32 v[46:47], v[46:47], v[56:57]
	s_nop 4
	v_cvt_pk_bf16_f32 v48, v48, v49
	v_cvt_pk_bf16_f32 v49, v50, v51
	ds_write_b64 v200, v[48:49] offset:96
	ds_read_b128 v[48:51], v188 offset:52992
	ds_read_b128 v[52:55], v188 offset:53056
	s_waitcnt lgkmcnt(1)
	v_mfma_f32_16x16x32_bf16 v[44:47], v[48:51], v[96:99], v[44:47]
	s_waitcnt lgkmcnt(0)
	v_cndmask_b32_e64 v51, v55, 0, s[8:9]
	v_cndmask_b32_e64 v50, v54, 0, s[8:9]
	v_cndmask_b32_e64 v49, v53, 0, s[8:9]
	v_cndmask_b32_e64 v48, v52, 0, s[8:9]
	ds_read_b64 v[52:53], v92 offset:59392
	v_mov_b32_e32 v54, v28
	v_mfma_f32_16x16x32_bf16 v[44:47], v[48:51], v[60:63], v[44:47]
	v_mov_b32_e32 v55, v28
	v_lshlrev_b32_e32 v96, 2, v78
	v_mad_u64_u32 v[152:153], s[8:9], v69, s82, v[68:69]
	s_nop 4
	v_cvt_pk_bf16_f32 v44, v44, v45
	v_cvt_pk_bf16_f32 v45, v46, v47
	v_mov_b32_e32 v46, v28
	v_mov_b32_e32 v47, v28
	s_waitcnt lgkmcnt(0)
	s_nop 0
	v_mfma_f32_16x16x32_bf16 v[44:47], v[52:55], v[44:47], 0
	s_nop 7
	v_cvt_pk_bf16_f32 v44, v44, v45
	v_cvt_pk_bf16_f32 v45, v46, v47
	ds_write_b64 v200, v[44:45] offset:2400
	s_waitcnt lgkmcnt(0)
	s_barrier
	ds_read_b128 v[44:47], v96 offset:61440
	ds_read_b128 v[48:51], v96 offset:61456
	ds_read_b128 v[52:55], v96 offset:61472
	ds_read_b128 v[56:59], v96 offset:61488
	s_waitcnt lgkmcnt(3)
	v_sub_f32_e32 v44, v111, v44
	v_mul_f32_e32 v44, 0x3fb8aa3b, v44
	v_exp_f32_e32 v60, v44
	v_sub_f32_e32 v44, v111, v45
	v_mul_f32_e32 v44, 0x3fb8aa3b, v44
	v_exp_f32_e32 v61, v44
	v_sub_f32_e32 v44, v111, v46
	v_mul_f32_e32 v44, 0x3fb8aa3b, v44
	v_exp_f32_e32 v62, v44
	v_sub_f32_e32 v44, v111, v47
	v_mul_f32_e32 v44, 0x3fb8aa3b, v44
	v_exp_f32_e32 v63, v44
	s_waitcnt lgkmcnt(2)
	v_sub_f32_e32 v44, v111, v48
	v_mul_f32_e32 v44, 0x3fb8aa3b, v44
	v_exp_f32_e32 v88, v44
	v_sub_f32_e32 v44, v111, v49
	v_mul_f32_e32 v44, 0x3fb8aa3b, v44
	v_exp_f32_e32 v89, v44
	v_sub_f32_e32 v44, v111, v50
	v_mul_f32_e32 v44, 0x3fb8aa3b, v44
	v_exp_f32_e32 v90, v44
	v_sub_f32_e32 v44, v111, v51
	v_mul_f32_e32 v44, 0x3fb8aa3b, v44
	v_exp_f32_e32 v91, v44
	s_waitcnt lgkmcnt(1)
	v_sub_f32_e32 v44, v111, v52
	v_mul_f32_e32 v44, 0x3fb8aa3b, v44
	v_exp_f32_e32 v92, v44
	v_sub_f32_e32 v44, v111, v53
	v_mul_f32_e32 v44, 0x3fb8aa3b, v44
	v_exp_f32_e32 v93, v44
	v_sub_f32_e32 v44, v111, v54
	v_mul_f32_e32 v44, 0x3fb8aa3b, v44
	v_exp_f32_e32 v94, v44
	v_sub_f32_e32 v44, v111, v55
	v_mul_f32_e32 v44, 0x3fb8aa3b, v44
	v_exp_f32_e32 v95, v44
	s_waitcnt lgkmcnt(0)
	v_sub_f32_e32 v44, v111, v56
	v_mul_f32_e32 v44, 0x3fb8aa3b, v44
	v_exp_f32_e32 v56, v44
	v_sub_f32_e32 v44, v111, v57
	v_mul_f32_e32 v44, 0x3fb8aa3b, v44
	v_exp_f32_e32 v57, v44
	v_sub_f32_e32 v44, v111, v58
	v_mul_f32_e32 v44, 0x3fb8aa3b, v44
	v_exp_f32_e32 v58, v44
	v_sub_f32_e32 v44, v111, v59
	v_mul_f32_e32 v48, 0x3fb8aa3b, v44
	ds_read_b128 v[44:47], v96 offset:61952
	v_exp_f32_e32 v59, v48
	v_mul_lo_u32 v48, v29, s92
	v_lshl_add_u32 v97, v167, 1, v48
	ds_read_b128 v[48:51], v96 offset:61968
	s_waitcnt lgkmcnt(1)
	v_pk_mul_f32 v[44:45], v[44:45], v[60:61]
	ds_read_u16 v52, v97 offset:9216
	ds_read_u16 v53, v97 offset:9360
	ds_read_u16 v54, v97 offset:9504
	ds_read_u16 v55, v97 offset:9648
	ds_read_u16 v60, v97 offset:9792
	ds_read_u16 v61, v97 offset:9936
	ds_read_u16 v98, v97 offset:10080
	ds_read_u16 v99, v97 offset:10224
	s_waitcnt lgkmcnt(6)
	v_lshlrev_b32_e32 v53, 16, v53
	v_lshlrev_b32_e32 v52, 16, v52
	v_pk_mul_f32 v[44:45], v[44:45], v[52:53]
	v_pk_mul_f32 v[46:47], v[46:47], v[62:63]
	s_waitcnt lgkmcnt(4)
	v_lshlrev_b32_e32 v53, 16, v55
	v_lshlrev_b32_e32 v52, 16, v54
	v_pk_mul_f32 v[46:47], v[46:47], v[52:53]
	v_cvt_pk_bf16_f32 v44, v44, v45
	v_cvt_pk_bf16_f32 v45, v46, v47
	v_pk_mul_f32 v[46:47], v[48:49], v[88:89]
	s_waitcnt lgkmcnt(2)
	v_lshlrev_b32_e32 v49, 16, v61
	v_lshlrev_b32_e32 v48, 16, v60
	v_pk_mul_f32 v[46:47], v[46:47], v[48:49]
	v_pk_mul_f32 v[52:53], v[50:51], v[90:91]
	ds_read_b128 v[48:51], v96 offset:61984
	s_waitcnt lgkmcnt(1)
	v_lshlrev_b32_e32 v55, 16, v99
	v_lshlrev_b32_e32 v54, 16, v98
	v_pk_mul_f32 v[52:53], v[52:53], v[54:55]
	v_cvt_pk_bf16_f32 v46, v46, v47
	v_cvt_pk_bf16_f32 v47, v52, v53
	ds_read_b128 v[52:55], v96 offset:62000
	ds_read_u16 v60, v97 offset:10368
	ds_read_u16 v61, v97 offset:10512
	ds_read_u16 v62, v97 offset:10656
	ds_read_u16 v63, v97 offset:10800
	ds_read_u16 v88, v97 offset:10944
	ds_read_u16 v89, v97 offset:11088
	ds_read_u16 v90, v97 offset:11232
	ds_read_u16 v91, v97 offset:11376
	s_waitcnt lgkmcnt(9)
	v_pk_mul_f32 v[48:49], v[48:49], v[92:93]
	s_waitcnt lgkmcnt(6)
	v_lshlrev_b32_e32 v61, 16, v61
	v_lshlrev_b32_e32 v60, 16, v60
	v_pk_mul_f32 v[48:49], v[48:49], v[60:61]
	v_pk_mul_f32 v[50:51], v[50:51], v[94:95]
	s_waitcnt lgkmcnt(4)
	v_lshlrev_b32_e32 v61, 16, v63
	v_lshlrev_b32_e32 v60, 16, v62
	v_pk_mul_f32 v[50:51], v[50:51], v[60:61]
	v_cvt_pk_bf16_f32 v48, v48, v49
	v_cvt_pk_bf16_f32 v49, v50, v51
	v_pk_mul_f32 v[50:51], v[52:53], v[56:57]
	s_waitcnt lgkmcnt(2)
	v_lshlrev_b32_e32 v53, 16, v89
	v_lshlrev_b32_e32 v52, 16, v88
	v_pk_mul_f32 v[50:51], v[50:51], v[52:53]
	v_pk_mul_f32 v[52:53], v[54:55], v[58:59]
	s_waitcnt lgkmcnt(0)
	v_lshlrev_b32_e32 v55, 16, v91
	v_lshlrev_b32_e32 v54, 16, v90
	v_pk_mul_f32 v[52:53], v[52:53], v[54:55]
	v_cvt_pk_bf16_f32 v50, v50, v51
	v_cvt_pk_bf16_f32 v51, v52, v53
	v_lshlrev_b32_e32 v52, 1, v78
	v_mad_u32_u24 v52, v167, s82, v52
	ds_write_b128 v52, v[44:47] offset:18432
	ds_write_b128 v52, v[48:51] offset:18448
	ds_read_b128 v[44:47], v152
	ds_read_b128 v[48:51], v188 offset:9216
	ds_read_b128 v[52:55], v152 offset:64
	ds_read_b128 v[56:59], v188 offset:9280
	s_waitcnt lgkmcnt(2)
	v_mfma_f32_16x16x32_bf16 v[48:51], v[44:47], v[48:51], 0
	ds_read_b128 v[60:63], v188 offset:11520
	ds_read_b128 v[88:91], v188 offset:11584
	ds_read_b128 v[92:95], v188 offset:13824
	ds_read_b128 v[96:99], v188 offset:13888
	ds_read_b128 v[100:103], v188 offset:16128
	ds_read_b128 v[104:107], v188 offset:16192
	s_waitcnt lgkmcnt(6)
	v_mfma_f32_16x16x32_bf16 v[48:51], v[52:55], v[56:59], v[48:51]
	v_mul_f32_e32 v111, 0x3fb8aa3b, v111
	s_waitcnt lgkmcnt(5)
	v_mfma_f32_16x16x32_bf16 v[60:63], v[44:47], v[60:63], 0
	s_waitcnt lgkmcnt(4)
	v_mfma_f32_16x16x32_bf16 v[56:59], v[52:55], v[88:91], v[60:63]
	s_nop 2
	v_mul_f32_e32 v48, v36, v48
	v_mul_f32_e32 v48, v72, v48
	v_mul_f32_e32 v48, v79, v48
	v_cvt_pk_bf16_f32 v48, v48, s0
	v_cndmask_b32_e64 v48, v48, 0, vcc
	ds_write_b16 v64, v48 offset:46080
	v_mul_f32_e32 v48, v37, v49
	v_mul_f32_e32 v48, v72, v48
	v_mul_f32_e32 v48, v80, v48
	v_cvt_pk_bf16_f32 v48, v48, s0
	v_cmp_ge_i32_e32 vcc, v169, v109
	s_waitcnt lgkmcnt(4)
	v_mfma_f32_16x16x32_bf16 v[92:95], v[44:47], v[92:95], 0
	v_cndmask_b32_e32 v48, 0, v48, vcc
	ds_write_b16 v64, v48 offset:46224
	v_mul_f32_e32 v48, v38, v50
	v_mul_f32_e32 v48, v72, v48
	v_mul_f32_e32 v48, v65, v48
	v_cvt_pk_bf16_f32 v48, v48, s0
	v_cmp_ge_i32_e32 vcc, v170, v109
	s_waitcnt lgkmcnt(4)
	v_mfma_f32_16x16x32_bf16 v[60:63], v[52:55], v[96:99], v[92:95]
	v_cndmask_b32_e32 v48, 0, v48, vcc
	ds_write_b16 v64, v48 offset:46368
	v_mul_f32_e32 v48, v39, v51
	v_mul_f32_e32 v48, v72, v48
	v_mul_f32_e32 v48, v66, v48
	v_cvt_pk_bf16_f32 v48, v48, s0
	v_cmp_ge_i32_e32 vcc, v171, v109
	s_waitcnt lgkmcnt(4)
	v_mfma_f32_16x16x32_bf16 v[44:47], v[44:47], v[100:103], 0
	v_cndmask_b32_e32 v48, 0, v48, vcc
	ds_write_b16 v64, v48 offset:46512
	v_mul_f32_e32 v48, v36, v56
	v_mul_f32_e32 v48, v73, v48
	v_mul_f32_e32 v48, v67, v48
	v_cvt_pk_bf16_f32 v48, v48, s0
	v_cndmask_b32_e64 v48, v48, 0, s[0:1]
	ds_write_b16 v64, v48 offset:46112
	v_mul_f32_e32 v48, v37, v57
	v_mul_f32_e32 v48, v73, v48
	v_mul_f32_e32 v48, v76, v48
	v_cvt_pk_bf16_f32 v48, v48, s0
	v_cmp_ge_i32_e32 vcc, v169, v172
	s_waitcnt lgkmcnt(5)
	v_mfma_f32_16x16x32_bf16 v[44:47], v[52:55], v[104:107], v[44:47]
	s_and_b32 s1, s94, 0xfffffc00
	v_cndmask_b32_e32 v48, 0, v48, vcc
	ds_write_b16 v64, v48 offset:46256
	v_mul_f32_e32 v48, v38, v58
	v_mul_f32_e32 v48, v73, v48
	v_mul_f32_e32 v48, v81, v48
	v_cvt_pk_bf16_f32 v48, v48, s0
	v_cmp_ge_i32_e32 vcc, v170, v172
	v_mul_f32_e32 v44, v36, v44
	v_mul_f32_e32 v44, v71, v44
	v_cndmask_b32_e32 v48, 0, v48, vcc
	ds_write_b16 v64, v48 offset:46400
	v_mul_f32_e32 v48, v39, v59
	v_mul_f32_e32 v48, v73, v48
	v_mul_f32_e32 v48, v77, v48
	v_cvt_pk_bf16_f32 v48, v48, s0
	v_cmp_ge_i32_e32 vcc, v171, v172
	v_mul_f32_e32 v44, v85, v44
	v_cvt_pk_bf16_f32 v44, v44, s0
	v_cndmask_b32_e32 v48, 0, v48, vcc
	ds_write_b16 v64, v48 offset:46544
	v_mul_f32_e32 v48, v36, v60
	v_mul_f32_e32 v48, v70, v48
	v_mul_f32_e32 v48, v82, v48
	v_cvt_pk_bf16_f32 v48, v48, s0
	v_cndmask_b32_e64 v48, v48, 0, s[4:5]
	ds_write_b16 v64, v48 offset:46144
	v_mul_f32_e32 v48, v37, v61
	v_mul_f32_e32 v48, v70, v48
	v_mul_f32_e32 v48, v83, v48
	v_cvt_pk_bf16_f32 v48, v48, s0
	v_cmp_ge_i32_e32 vcc, v169, v173
	v_cndmask_b32_e64 v44, v44, 0, s[6:7]
	ds_write_b16 v64, v44 offset:46176
	v_cndmask_b32_e32 v48, 0, v48, vcc
	ds_write_b16 v64, v48 offset:46288
	v_mul_f32_e32 v48, v38, v62
	v_mul_f32_e32 v48, v70, v48
	v_mul_f32_e32 v48, v84, v48
	v_cvt_pk_bf16_f32 v48, v48, s0
	v_cmp_ge_i32_e32 vcc, v170, v173
	v_mul_f32_e32 v44, v37, v45
	v_mul_f32_e32 v44, v71, v44
	v_cndmask_b32_e32 v48, 0, v48, vcc
	ds_write_b16 v64, v48 offset:46432
	v_mul_f32_e32 v48, v39, v63
	v_mul_f32_e32 v48, v70, v48
	v_mul_f32_e32 v48, v74, v48
	v_cvt_pk_bf16_f32 v48, v48, s0
	v_cmp_ge_i32_e32 vcc, v171, v173
	v_mul_f32_e32 v44, v86, v44
	v_cvt_pk_bf16_f32 v44, v44, s0
	v_cndmask_b32_e32 v48, 0, v48, vcc
	v_cmp_ge_i32_e32 vcc, v169, v174
	ds_write_b16 v64, v48 offset:46576
	v_mul_u32_u24_e32 v48, 0x48, v109
	v_cndmask_b32_e32 v44, 0, v44, vcc
	ds_write_b16 v64, v44 offset:46320
	v_mul_f32_e32 v44, v38, v46
	v_mul_f32_e32 v44, v71, v44
	v_mul_f32_e32 v44, v87, v44
	v_cvt_pk_bf16_f32 v44, v44, s0
	v_cmp_ge_i32_e32 vcc, v170, v174
	v_lshl_add_u32 v96, v48, 1, v68
	s_nop 0
	v_cndmask_b32_e32 v44, 0, v44, vcc
	ds_write_b16 v64, v44 offset:46464
	v_mul_f32_e32 v44, v39, v47
	v_mul_f32_e32 v44, v71, v44
	v_mul_f32_e32 v44, v75, v44
	v_cvt_pk_bf16_f32 v44, v44, s0
	v_cmp_ge_i32_e32 vcc, v171, v174
	s_lshl_b32 s0, s94, 7
	s_and_b32 s0, s0, 0x380
	v_cndmask_b32_e32 v44, 0, v44, vcc
	ds_write_b16 v64, v44 offset:46608
	s_waitcnt lgkmcnt(0)
	s_barrier
	ds_read_b128 v[44:47], v152 offset:18432
	ds_read_b128 v[48:51], v96 offset:27648
	ds_read_b128 v[56:59], v152 offset:18496
	ds_read_b128 v[52:55], v96 offset:27712
	ds_read_b128 v[64:67], v96 offset:36864
	ds_read_b128 v[68:71], v96 offset:36928
	ds_read_b128 v[76:79], v152 offset:46080
	ds_read_b128 v[176:179], v152 offset:46144
	ds_read_b128 v[80:83], v96 offset:29952
	ds_read_b128 v[84:87], v96 offset:30016
	ds_read_b128 v[92:95], v96 offset:39168
	ds_read_b128 v[184:187], v96 offset:39232
	s_waitcnt lgkmcnt(3)
	v_mfma_f32_16x16x32_bf16 v[88:91], v[44:47], v[80:83], 0
	s_or_b32 s0, s0, s1
	s_and_b32 s1, s68, 0x7f
	s_or_b32 s0, s0, s1
	s_waitcnt lgkmcnt(1)
	v_mfma_f32_16x16x32_bf16 v[188:191], v[44:47], v[92:95], 0
	s_cmpk_lt_i32 s68, 0x200
	s_cselect_b32 s0, s0, s94
	s_ashr_i32 s1, s0, 31
	v_mfma_f32_16x16x32_bf16 v[192:195], v[76:79], v[80:83], 0
	ds_read_b128 v[80:83], v96 offset:32256
	ds_read_b128 v[200:203], v96 offset:32320
	s_lshl_b64 s[4:5], s[0:1], 13
	v_cmp_eq_u32_e32 vcc, v168, v109
	v_mfma_f32_16x16x32_bf16 v[196:199], v[76:79], v[92:95], 0
	ds_read_b128 v[92:95], v96 offset:41472
	ds_read_b128 v[208:211], v96 offset:41536
	s_add_u32 s0, s77, s4
	s_addc_u32 s1, s78, s5
	s_waitcnt lgkmcnt(3)
	v_mfma_f32_16x16x32_bf16 v[204:207], v[44:47], v[80:83], 0
	s_add_u32 s6, s75, s4
	s_addc_u32 s7, s76, s5
	s_add_u32 s8, s29, s4
	s_waitcnt lgkmcnt(1)
	v_mfma_f32_16x16x32_bf16 v[212:215], v[44:47], v[92:95], 0
	s_addc_u32 s9, s74, s5
	s_add_u32 s4, s50, s4
	s_addc_u32 s5, s51, s5
	v_mfma_f32_16x16x32_bf16 v[216:219], v[76:79], v[80:83], 0
	ds_read_b128 v[80:83], v96 offset:34560
	ds_read_b128 v[224:227], v96 offset:34624
	s_mov_b32 s94, s93
	v_mfma_f32_16x16x32_bf16 v[220:223], v[76:79], v[92:95], 0
	ds_read_b128 v[92:95], v96 offset:43776
	ds_read_b128 v[232:235], v96 offset:43840
	v_mfma_f32_16x16x32_bf16 v[60:63], v[44:47], v[48:51], 0
	v_mfma_f32_16x16x32_bf16 v[72:75], v[44:47], v[64:67], 0
	v_mfma_f32_16x16x32_bf16 v[48:51], v[76:79], v[48:51], 0
	v_mfma_f32_16x16x32_bf16 v[64:67], v[76:79], v[64:67], 0
	s_waitcnt lgkmcnt(3)
	v_mfma_f32_16x16x32_bf16 v[228:231], v[44:47], v[80:83], 0
	v_mfma_f32_16x16x32_bf16 v[236:239], v[76:79], v[80:83], 0
	s_waitcnt lgkmcnt(1)
	v_mfma_f32_16x16x32_bf16 v[240:243], v[76:79], v[92:95], 0
	v_mfma_f32_16x16x32_bf16 v[80:83], v[56:59], v[184:187], v[188:191]
	v_mfma_f32_16x16x32_bf16 v[76:79], v[176:179], v[184:187], v[196:199]
	v_exp_f32_e32 v184, v111
	v_lshlrev_b32_e32 v185, 6, v168
	v_or_b32_e32 v152, v185, v109
	v_mfma_f32_16x16x32_bf16 v[44:47], v[44:47], v[92:95], 0
	v_cndmask_b32_e32 v111, 0, v184, vcc
	v_ashrrev_i32_e32 v153, 31, v152
	v_cmp_eq_u32_e32 vcc, v169, v109
	v_mfma_f32_16x16x32_bf16 v[104:107], v[56:59], v[52:55], v[60:63]
	v_cvt_pk_bf16_f32 v80, v80, v81
	v_cvt_pk_bf16_f32 v81, v82, v83
	v_cvt_pk_bf16_f32 v76, v76, v77
	v_mfma_f32_16x16x32_bf16 v[96:99], v[56:59], v[68:71], v[72:75]
	v_cvt_pk_bf16_f32 v77, v78, v79
	s_nop 2
	v_sub_f32_e32 v104, v111, v104
	v_cvt_pk_bf16_f32 v104, v104, s0
	v_mfma_f32_16x16x32_bf16 v[100:103], v[176:179], v[52:55], v[48:51]
	v_lshl_add_u32 v111, v109, 1, v175
	v_exp_f32_e32 v175, v40
	s_waitcnt vmcnt(5)
	v_mov_b64_e32 v[78:79], v[132:133]
	v_mfma_f32_16x16x32_bf16 v[92:95], v[176:179], v[68:71], v[64:67]
	v_mov_b32_e32 v82, v116
	v_mov_b32_e32 v83, v114
	v_mfma_f32_16x16x32_bf16 v[88:91], v[56:59], v[84:87], v[88:91]
	v_mfma_f32_16x16x32_bf16 v[84:87], v[176:179], v[84:87], v[192:195]
	v_mfma_f32_16x16x32_bf16 v[72:75], v[56:59], v[200:203], v[204:207]
	s_nop 1
	v_lshlrev_b32_e32 v192, 6, v169
	v_exp_f32_e32 v193, v41
	v_mfma_f32_16x16x32_bf16 v[60:63], v[56:59], v[208:211], v[212:215]
	v_mfma_f32_16x16x32_bf16 v[68:71], v[176:179], v[200:203], v[216:219]
	v_mfma_f32_16x16x32_bf16 v[64:67], v[176:179], v[208:211], v[220:223]
	s_nop 5
	v_cvt_pk_bf16_f32 v60, v60, v61
	v_cvt_pk_bf16_f32 v61, v62, v63
	s_waitcnt vmcnt(0)
	v_mov_b32_e32 v62, v148
	v_mfma_f32_16x16x32_bf16 v[52:55], v[56:59], v[224:227], v[228:231]
	s_waitcnt lgkmcnt(0)
	v_mfma_f32_16x16x32_bf16 v[44:47], v[56:59], v[232:235], v[44:47]
	v_mfma_f32_16x16x32_bf16 v[56:59], v[176:179], v[224:227], v[236:239]
	v_mfma_f32_16x16x32_bf16 v[48:51], v[176:179], v[232:235], v[240:243]
	v_lshlrev_b64 v[176:177], 1, v[152:153]
	v_lshl_add_u64 v[178:179], s[0:1], 0, v[176:177]
	global_store_short v[178:179], v104, off
	ds_read_u16 v40, v111
	ds_read_u16 v186, v111 offset:32
	ds_read_u16 v153, v111 offset:144
	ds_read_u16 v187, v111 offset:176
	ds_read_u16 v188, v111 offset:64
	ds_read_u16 v189, v111 offset:208
	ds_read_u16 v190, v111 offset:240
	ds_read_u16 v191, v111 offset:96
	s_waitcnt lgkmcnt(7)
	v_lshlrev_b32_e32 v40, 16, v40
	v_mul_f32_e32 v40, v36, v40
	v_fma_f32 v40, v175, v40, -v100
	v_cvt_pk_bf16_f32 v40, v40, s0
	v_lshl_add_u64 v[176:177], s[4:5], 0, v[176:177]
	global_store_short v[176:177], v40, off
	v_cndmask_b32_e32 v40, 0, v184, vcc
	v_or_b32_e32 v104, v192, v109
	v_sub_f32_e32 v40, v40, v105
	v_ashrrev_i32_e32 v105, 31, v104
	v_lshlrev_b64 v[176:177], 1, v[104:105]
	v_cvt_pk_bf16_f32 v40, v40, s0
	v_lshl_add_u64 v[178:179], s[0:1], 0, v[176:177]
	global_store_short v[178:179], v40, off
	s_waitcnt lgkmcnt(5)
	v_lshlrev_b32_e32 v40, 16, v153
	v_mul_f32_e32 v40, v37, v40
	v_fma_f32 v40, v193, v40, -v101
	v_cvt_pk_bf16_f32 v100, v40, s0
	v_lshl_add_u64 v[40:41], s[4:5], 0, v[176:177]
	v_cmp_eq_u32_e32 vcc, v170, v109
	global_store_short v[40:41], v100, off
	v_lshlrev_b32_e32 v178, 6, v170
	v_cndmask_b32_e32 v40, 0, v184, vcc
	v_sub_f32_e32 v40, v40, v106
	v_cvt_pk_bf16_f32 v105, v40, s0
	v_or_b32_e32 v40, v178, v109
	v_ashrrev_i32_e32 v41, 31, v40
	v_lshlrev_b64 v[100:101], 1, v[40:41]
	v_lshl_add_u64 v[176:177], s[0:1], 0, v[100:101]
	v_mul_f32_e32 v41, 0x3fb8aa3b, v42
	global_store_short v[176:177], v105, off
	v_exp_f32_e32 v179, v41
	ds_read_u16 v41, v111 offset:288
	ds_read_u16 v42, v111 offset:432
	ds_read_u16 v194, v111 offset:320
	ds_read_u16 v195, v111 offset:464
	ds_read_u16 v196, v111 offset:352
	ds_read_u16 v197, v111 offset:496
	ds_read_u16 v198, v111 offset:528
	ds_read_u16 v199, v111 offset:384
	s_waitcnt lgkmcnt(7)
	v_lshlrev_b32_e32 v41, 16, v41
	v_mul_f32_e32 v41, v38, v41
	v_fma_f32 v41, v179, v41, -v102
	v_cvt_pk_bf16_f32 v41, v41, s0
	v_lshl_add_u64 v[100:101], s[4:5], 0, v[100:101]
	v_lshlrev_b32_e32 v102, 6, v171
	global_store_short v[100:101], v41, off
	v_cmp_eq_u32_e32 vcc, v171, v109
	v_or_b32_e32 v100, v102, v109
	v_ashrrev_i32_e32 v101, 31, v100
	v_cndmask_b32_e32 v41, 0, v184, vcc
	v_sub_f32_e32 v41, v41, v107
	v_lshlrev_b64 v[106:107], 1, v[100:101]
	v_exp_f32_e32 v109, v43
	v_cvt_pk_bf16_f32 v41, v41, s0
	v_lshl_add_u64 v[176:177], s[0:1], 0, v[106:107]
	global_store_short v[176:177], v41, off
	s_waitcnt lgkmcnt(6)
	v_lshlrev_b32_e32 v41, 16, v42
	v_mul_f32_e32 v41, v39, v41
	v_fma_f32 v41, v109, v41, -v103
	v_cvt_pk_bf16_f32 v41, v41, s0
	v_lshl_add_u64 v[42:43], s[4:5], 0, v[106:107]
	v_ashrrev_i32_e32 v111, 31, v110
	global_store_short v[42:43], v41, off
	v_cvt_pk_bf16_f32 v42, v96, v97
	v_cvt_pk_bf16_f32 v43, v98, v99
	v_lshrrev_b32_e32 v96, 6, v181
	v_lshlrev_b32_e32 v96, 11, v96
	v_and_b32_e32 v97, 63, v181
	v_lshl_or_b32 v96, v97, 4, v96
	v_mov_b32_e32 v97, 0
	v_lshl_add_u64 v[96:97], v[96:97], 0, s[8:9]
	v_lshlrev_b32_e32 v41, 2, v167
	global_store_dwordx2 v[96:97], v[42:43], off
	v_cvt_pk_bf16_f32 v42, v92, v93
	v_lshl_or_b32 v92, v29, 10, v41
	v_ashrrev_i32_e32 v93, 31, v92
	v_cmp_eq_u32_e32 vcc, v168, v172
	v_cvt_pk_bf16_f32 v43, v94, v95
	v_lshl_add_u64 v[92:93], v[92:93], 1, s[6:7]
	v_cndmask_b32_e32 v29, 0, v184, vcc
	v_ashrrev_i32_e32 v153, 31, v185
	global_store_dwordx2 v[92:93], v[42:43], off
	v_sub_f32_e32 v29, v29, v88
	v_lshlrev_b64 v[42:43], 1, v[152:153]
	v_cvt_pk_bf16_f32 v29, v29, s0
	v_lshl_add_u64 v[94:95], s[0:1], 0, v[42:43]
	global_store_short v[94:95], v29, off offset:32
	v_lshlrev_b32_e32 v29, 16, v186
	v_mul_f32_e32 v29, v36, v29
	v_fma_f32 v29, v175, v29, -v84
	v_cvt_pk_bf16_f32 v29, v29, s0
	v_lshl_add_u64 v[42:43], s[4:5], 0, v[42:43]
	v_cmp_eq_u32_e32 vcc, v169, v172
	global_store_short v[42:43], v29, off offset:32
	v_ashrrev_i32_e32 v105, 31, v192
	v_cndmask_b32_e32 v29, 0, v184, vcc
	v_sub_f32_e32 v29, v29, v89
	v_lshlrev_b64 v[88:89], 1, v[104:105]
	v_cvt_pk_bf16_f32 v29, v29, s0
	v_lshl_add_u64 v[98:99], s[0:1], 0, v[88:89]
	global_store_short v[98:99], v29, off offset:32
	v_lshlrev_b32_e32 v29, 16, v187
	v_mul_f32_e32 v29, v37, v29
	v_fma_f32 v29, v193, v29, -v85
	v_cvt_pk_bf16_f32 v29, v29, s0
	v_lshl_add_u64 v[84:85], s[4:5], 0, v[88:89]
	v_cmp_eq_u32_e32 vcc, v170, v172
	global_store_short v[84:85], v29, off offset:32
	v_ashrrev_i32_e32 v41, 31, v178
	v_cndmask_b32_e32 v29, 0, v184, vcc
	v_sub_f32_e32 v29, v29, v90
	v_lshlrev_b64 v[40:41], 1, v[40:41]
	v_cvt_pk_bf16_f32 v29, v29, s0
	v_lshl_add_u64 v[88:89], s[0:1], 0, v[40:41]
	global_store_short v[88:89], v29, off offset:32
	s_waitcnt lgkmcnt(5)
	v_lshlrev_b32_e32 v29, 16, v194
	v_mul_f32_e32 v29, v38, v29
	v_fma_f32 v29, v179, v29, -v86
	v_cvt_pk_bf16_f32 v29, v29, s0
	v_lshl_add_u64 v[40:41], s[4:5], 0, v[40:41]
	v_cmp_eq_u32_e32 vcc, v171, v172
	global_store_short v[40:41], v29, off offset:32
	v_ashrrev_i32_e32 v101, 31, v102
	v_cndmask_b32_e32 v29, 0, v184, vcc
	v_sub_f32_e32 v29, v29, v91
	v_lshlrev_b64 v[90:91], 1, v[100:101]
	v_cvt_pk_bf16_f32 v29, v29, s0
	v_lshl_add_u64 v[100:101], s[0:1], 0, v[90:91]
	global_store_short v[100:101], v29, off offset:32
	s_waitcnt lgkmcnt(4)
	v_lshlrev_b32_e32 v29, 16, v195
	v_mul_f32_e32 v29, v39, v29
	v_fma_f32 v29, v109, v29, -v87
	v_cvt_pk_bf16_f32 v29, v29, s0
	v_lshl_add_u64 v[86:87], s[4:5], 0, v[90:91]
	v_cmp_eq_u32_e32 vcc, v168, v173
	global_store_short v[86:87], v29, off offset:32
	global_store_dwordx2 v[96:97], v[80:81], off offset:8
	v_cndmask_b32_e32 v29, 0, v184, vcc
	v_sub_f32_e32 v29, v29, v72
	v_cvt_pk_bf16_f32 v29, v29, s0
	global_store_dwordx2 v[92:93], v[76:77], off offset:512
	global_store_short v[94:95], v29, off offset:64
	v_lshlrev_b32_e32 v29, 16, v188
	v_mul_f32_e32 v29, v36, v29
	v_fma_f32 v29, v175, v29, -v68
	v_cvt_pk_bf16_f32 v29, v29, s0
	v_cmp_eq_u32_e32 vcc, v169, v173
	global_store_short v[42:43], v29, off offset:64
	v_mov_b32_e32 v77, v115
	v_cndmask_b32_e32 v29, 0, v184, vcc
	v_sub_f32_e32 v29, v29, v73
	v_cvt_pk_bf16_f32 v29, v29, s0
	global_store_short v[98:99], v29, off offset:64
	v_lshlrev_b32_e32 v29, 16, v189
	v_mul_f32_e32 v29, v37, v29
	v_fma_f32 v29, v193, v29, -v69
	v_cvt_pk_bf16_f32 v29, v29, s0
	v_cmp_eq_u32_e32 vcc, v170, v173
	global_store_short v[84:85], v29, off offset:64
	v_mov_b32_e32 v73, v117
	v_cndmask_b32_e32 v29, 0, v184, vcc
	v_sub_f32_e32 v29, v29, v74
	v_cvt_pk_bf16_f32 v29, v29, s0
	global_store_short v[88:89], v29, off offset:64
	s_waitcnt lgkmcnt(3)
	v_lshlrev_b32_e32 v29, 16, v196
	v_mul_f32_e32 v29, v38, v29
	v_fma_f32 v29, v179, v29, -v70
	v_cvt_pk_bf16_f32 v29, v29, s0
	v_cmp_eq_u32_e32 vcc, v171, v173
	global_store_short v[40:41], v29, off offset:64
	v_mov_b64_e32 v[90:91], v[130:131]
	v_cndmask_b32_e32 v29, 0, v184, vcc
	v_sub_f32_e32 v29, v29, v75
	v_cvt_pk_bf16_f32 v29, v29, s0
	global_store_short v[100:101], v29, off offset:64
	s_waitcnt lgkmcnt(2)
	v_lshlrev_b32_e32 v29, 16, v197
	v_mul_f32_e32 v29, v39, v29
	v_fma_f32 v29, v109, v29, -v71
	v_cvt_pk_bf16_f32 v29, v29, s0
	v_cmp_eq_u32_e32 vcc, v168, v174
	global_store_short v[86:87], v29, off offset:64
	global_store_dwordx2 v[96:97], v[60:61], off offset:1024
	v_cndmask_b32_e32 v29, 0, v184, vcc
	v_sub_f32_e32 v29, v29, v52
	v_cvt_pk_bf16_f32 v60, v64, v65
	v_cvt_pk_bf16_f32 v61, v66, v67
	v_cvt_pk_bf16_f32 v29, v29, s0
	global_store_dwordx2 v[92:93], v[60:61], off offset:1024
	global_store_short v[94:95], v29, off offset:96
	v_lshlrev_b32_e32 v29, 16, v191
	v_mul_f32_e32 v29, v36, v29
	v_fma_f32 v29, v175, v29, -v56
	v_cvt_pk_bf16_f32 v29, v29, s0
	v_cmp_eq_u32_e32 vcc, v169, v174
	global_store_short v[42:43], v29, off offset:96
	v_cvt_pk_bf16_f32 v36, v44, v45
	v_cndmask_b32_e32 v29, 0, v184, vcc
	v_sub_f32_e32 v29, v29, v53
	v_cvt_pk_bf16_f32 v29, v29, s0
	global_store_short v[98:99], v29, off offset:96
	v_lshlrev_b32_e32 v29, 16, v190
	v_mul_f32_e32 v29, v37, v29
	v_fma_f32 v29, v193, v29, -v57
	v_cvt_pk_bf16_f32 v29, v29, s0
	v_cmp_eq_u32_e32 vcc, v170, v174
	global_store_short v[84:85], v29, off offset:96
	v_cvt_pk_bf16_f32 v37, v46, v47
	v_cndmask_b32_e32 v29, 0, v184, vcc
	v_sub_f32_e32 v29, v29, v54
	v_cvt_pk_bf16_f32 v29, v29, s0
	global_store_short v[88:89], v29, off offset:96
	s_waitcnt lgkmcnt(0)
	v_lshlrev_b32_e32 v29, 16, v199
	v_mul_f32_e32 v29, v38, v29
	v_fma_f32 v29, v179, v29, -v58
	v_cvt_pk_bf16_f32 v29, v29, s0
	v_cmp_eq_u32_e32 vcc, v171, v174
	global_store_short v[40:41], v29, off offset:96
	v_mov_b32_e32 v99, v164
	v_cndmask_b32_e32 v29, 0, v184, vcc
	v_sub_f32_e32 v29, v29, v55
	v_cvt_pk_bf16_f32 v29, v29, s0
	global_store_short v[100:101], v29, off offset:96
	v_lshlrev_b32_e32 v29, 16, v198
	v_mul_f32_e32 v29, v39, v29
	v_fma_f32 v29, v109, v29, -v59
	v_cvt_pk_bf16_f32 v29, v29, s0
	global_store_short v[86:87], v29, off offset:96
	global_store_dwordx2 v[96:97], v[36:37], off offset:1032
	v_cvt_pk_bf16_f32 v36, v48, v49
	v_cvt_pk_bf16_f32 v37, v50, v51
	global_store_dwordx2 v[92:93], v[36:37], off offset:1536
	s_andn2_b64 vcc, exec, s[70:71]
	v_mov_b32_e32 v98, v163
	v_mov_b32_e32 v97, v165
	v_mov_b32_e32 v100, v166
	v_mov_b32_e32 v71, v113
	v_mov_b32_e32 v75, v31
	v_mov_b32_e32 v53, v125
	v_mov_b32_e32 v59, v123
	v_mov_b32_e32 v57, v129
	v_mov_b32_e32 v61, v127
	v_mov_b32_e32 v37, v141
	v_mov_b32_e32 v41, v139
	v_mov_b32_e32 v39, v145
	v_mov_b32_e32 v43, v143
	v_mov_b64_e32 v[86:87], v[120:121]
	v_mov_b64_e32 v[88:89], v[118:119]
	v_mov_b64_e32 v[68:69], v[134:135]
	v_mov_b64_e32 v[80:81], v[136:137]
	v_mov_b64_e32 v[50:51], v[150:151]
	v_mov_b64_e32 v[54:55], v[146:147]
	v_mov_b32_e32 v44, v144
	v_mov_b32_e32 v45, v142
	v_mov_b32_e32 v46, v140
	v_mov_b32_e32 v47, v138
	v_mov_b32_e32 v64, v128
	v_mov_b32_e32 v65, v126
	v_mov_b32_e32 v66, v124
	v_mov_b32_e32 v67, v122
	v_mov_b32_e32 v84, v112
	v_mov_b32_e32 v85, v30
	v_mov_b32_e32 v48, v149
	s_cbranch_vccz .LBB0_734

.LBB0_905:
	s_andn2_b64 vcc, exec, s[0:1]
	s_cbranch_vccnz .LBB0_931
	v_mov_b32_e32 v185, v181
	s_movk_i32 s0, 0x3c0
	v_ashrrev_i32_e32 v167, 6, v185
	v_lshlrev_b32_e32 v192, 10, v167
	v_lshlrev_b32_e32 v0, 6, v185
	v_and_or_b32 v0, v0, s0, v192
	v_lshrrev_b32_e32 v2, 1, v185
	v_ashrrev_i32_e32 v1, 31, v0
	v_and_b32_e32 v168, 24, v2
	v_lshl_add_u64 v[0:1], v[0:1], 1, s[20:21]
	s_waitcnt vmcnt(16)
	v_lshlrev_b32_e32 v160, 1, v168
	v_mov_b32_e32 v161, 0
	v_and_b32_e32 v166, 63, v185
	v_lshl_add_u64 v[0:1], v[0:1], 0, v[160:161]
	s_mov_b64 s[4:5], 0x11048000
	v_lshl_add_u64 v[176:177], v[0:1], 0, s[4:5]
	v_lshl_or_b32 v0, v166, 4, v192
	v_ashrrev_i32_e32 v1, 31, v0
	v_lshlrev_b64 v[162:163], 1, v[0:1]
	v_lshl_or_b32 v206, v166, 3, v192
	v_lshlrev_b32_e32 v206, 1, v206
	v_mov_b32_e32 v207, 0
	s_mov_b32 s1, 0
	v_lshl_add_u64 v[164:165], s[20:21], 0, v[162:163]
	s_mov_b64 s[4:5], 0x13148000
	s_lshl_b32 s0, s2, 19
	v_lshl_add_u64 v[178:179], s[20:21], 0, v[206:207]
	v_lshl_add_u64 v[178:179], v[178:179], 0, s[4:5]
	s_lshl_b64 s[4:5], s[0:1], 1
	v_lshl_add_u64 v[8:9], v[176:177], 0, s[4:5]
	v_lshl_add_u64 v[16:17], v[178:179], 0, s[4:5]
	s_or_b32 s4, s0, 0x1000
	s_mov_b32 s5, s1
	s_lshl_b64 s[4:5], s[4:5], 1
	v_lshl_add_u64 v[24:25], v[176:177], 0, s[4:5]
	v_lshl_add_u64 v[32:33], v[178:179], 0, s[4:5]
	s_or_b32 s4, s0, 0x2000
	s_mov_b32 s5, s1
	s_lshl_b64 s[4:5], s[4:5], 1
	v_lshl_add_u64 v[40:41], v[176:177], 0, s[4:5]
	v_lshl_add_u64 v[48:49], v[178:179], 0, s[4:5]
	s_or_b32 s4, s0, 0x3000
	s_mov_b32 s5, s1
	s_lshl_b64 s[4:5], s[4:5], 1
	v_lshl_add_u64 v[56:57], v[176:177], 0, s[4:5]
	v_lshl_add_u64 v[64:65], v[178:179], 0, s[4:5]
	s_or_b32 s4, s0, 0x4000
	s_mov_b32 s5, s1
	s_lshl_b64 s[4:5], s[4:5], 1
	v_lshl_add_u64 v[72:73], v[176:177], 0, s[4:5]
	v_lshl_add_u64 v[80:81], v[178:179], 0, s[4:5]
	s_or_b32 s4, s0, 0x5000
	s_mov_b32 s5, s1
	s_lshl_b64 s[4:5], s[4:5], 1
	v_lshl_add_u64 v[88:89], v[176:177], 0, s[4:5]
	v_lshl_add_u64 v[96:97], v[178:179], 0, s[4:5]
	s_or_b32 s4, s0, 0x6000
	s_mov_b32 s5, s1
	s_lshl_b64 s[4:5], s[4:5], 1
	v_lshl_add_u64 v[104:105], v[176:177], 0, s[4:5]
	v_lshl_add_u64 v[108:109], v[178:179], 0, s[4:5]
	s_or_b32 s4, s0, 0x7000
	s_mov_b32 s5, s1
	s_lshl_b64 s[4:5], s[4:5], 1
	v_lshl_add_u64 v[116:117], v[176:177], 0, s[4:5]
	v_lshl_add_u64 v[124:125], v[178:179], 0, s[4:5]
	s_or_b32 s4, s0, 0x8000
	s_mov_b32 s5, s1
	s_lshl_b64 s[4:5], s[4:5], 1
	v_lshl_add_u64 v[132:133], v[176:177], 0, s[4:5]
	v_lshl_add_u64 v[140:141], v[178:179], 0, s[4:5]
	s_or_b32 s4, s0, 0x9000
	s_mov_b32 s5, s1
	s_lshl_b64 s[4:5], s[4:5], 1
	v_lshl_add_u64 v[148:149], v[176:177], 0, s[4:5]
	v_lshl_add_u64 v[156:157], v[178:179], 0, s[4:5]
	s_barrier
	global_load_dwordx4 v[0:3], v[8:9], off
	global_load_dwordx4 v[4:7], v[8:9], off offset:64
	s_nop 0
	global_load_dwordx4 v[8:11], v[16:17], off offset:1024
	global_load_dwordx4 v[12:15], v[16:17], off
	s_nop 0
	global_load_dwordx4 v[16:19], v[24:25], off
	global_load_dwordx4 v[20:23], v[24:25], off offset:64
	s_nop 0
	global_load_dwordx4 v[24:27], v[32:33], off offset:1024
	global_load_dwordx4 v[28:31], v[32:33], off
	s_nop 0
	global_load_dwordx4 v[32:35], v[40:41], off
	global_load_dwordx4 v[36:39], v[40:41], off offset:64
	s_nop 0
	global_load_dwordx4 v[40:43], v[48:49], off offset:1024
	global_load_dwordx4 v[44:47], v[48:49], off
	s_nop 0
	global_load_dwordx4 v[48:51], v[56:57], off
	global_load_dwordx4 v[52:55], v[56:57], off offset:64
	s_nop 0
	global_load_dwordx4 v[56:59], v[64:65], off offset:1024
	global_load_dwordx4 v[60:63], v[64:65], off
	s_nop 0
	global_load_dwordx4 v[64:67], v[72:73], off
	global_load_dwordx4 v[68:71], v[72:73], off offset:64
	s_nop 0
	global_load_dwordx4 v[72:75], v[80:81], off offset:1024
	global_load_dwordx4 v[76:79], v[80:81], off
	s_nop 0
	global_load_dwordx4 v[80:83], v[88:89], off
	global_load_dwordx4 v[84:87], v[88:89], off offset:64
	s_nop 0
	global_load_dwordx4 v[88:91], v[96:97], off offset:1024
	global_load_dwordx4 v[92:95], v[96:97], off
	s_nop 0
	global_load_dwordx4 v[96:99], v[104:105], off
	global_load_dwordx4 v[100:103], v[104:105], off offset:64
	s_nop 0
	global_load_dwordx4 v[104:107], v[108:109], off offset:1024
	s_nop 0
	global_load_dwordx4 v[108:111], v[108:109], off
	s_nop 0
	global_load_dwordx4 v[112:115], v[116:117], off
	s_nop 0
	global_load_dwordx4 v[116:119], v[116:117], off offset:64
	s_nop 0
	global_load_dwordx4 v[120:123], v[124:125], off offset:1024
	s_nop 0
	global_load_dwordx4 v[124:127], v[124:125], off
	s_nop 0
	global_load_dwordx4 v[128:131], v[132:133], off
	s_nop 0
	global_load_dwordx4 v[132:135], v[132:133], off offset:64
	s_nop 0
	global_load_dwordx4 v[136:139], v[140:141], off offset:1024
	s_nop 0
	global_load_dwordx4 v[140:143], v[140:141], off
	s_nop 0
	global_load_dwordx4 v[144:147], v[148:149], off
	s_nop 0
	global_load_dwordx4 v[148:151], v[148:149], off offset:64
	s_nop 0
	global_load_dwordx4 v[152:155], v[156:157], off offset:1024
	s_nop 0
	global_load_dwordx4 v[156:159], v[156:157], off
	s_lshl_b32 s6, s2, 7
	s_mov_b64 s[4:5], 0x17348000
	s_mov_b32 s7, s1
	v_lshl_add_u64 v[186:187], s[20:21], 0, v[206:207]
	v_lshl_add_u64 v[186:187], v[186:187], 0, s[4:5]
	s_or_b32 s4, s0, 0x13000
	s_lshl_b32 s10, s2, 20
	s_lshl_b64 s[6:7], s[6:7], 13
	v_and_b32_e32 v184, 15, v185
	v_or_b32_e32 v166, 48, v166
	s_add_u32 s6, s20, s6
	v_mul_u32_u24_e32 v169, 0x48, v184
	v_mul_u32_u24_e32 v166, 0x48, v166
	s_addc_u32 s7, s21, s7
	v_lshl_or_b32 v164, v167, 5, v168
	v_lshlrev_b32_e32 v165, 1, v169
	v_lshlrev_b32_e32 v166, 1, v166
	v_lshl_add_u64 v[188:189], s[6:7], 0, v[206:207]
	v_mov_b32_e32 v162, v161
	v_mov_b32_e32 v163, v161
	v_add_u32_e32 v193, v164, v165
	v_add_u32_e32 v194, v164, v166
	v_add_u32_e32 v195, v165, v160
	v_add_u32_e32 v196, v166, v160
	v_mov_b32_e32 v160, v161
	v_mov_b64_e32 v[174:175], v[162:163]
	v_mov_b64_e32 v[170:171], v[162:163]
	v_mov_b64_e32 v[166:167], v[162:163]
	s_mov_b64 s[6:7], 0
	s_mov_b32 s11, 0x17348000
	s_mov_b32 s12, 0x1734a000
	s_mov_b32 s13, 0x1734c000
	s_mov_b32 s14, 0x1734e000
	s_mov_b32 s15, 0x17350000
	s_mov_b32 s16, 0x17352000
	s_mov_b32 s17, 0x17354000
	s_mov_b32 s29, 0x17356000
	v_mov_b64_e32 v[172:173], v[160:161]
	v_mov_b64_e32 v[168:169], v[160:161]
	v_mov_b64_e32 v[164:165], v[160:161]
	s_mov_b32 s34, 0
	s_branch .LBB0_908

.LBB0_908:
	v_lshl_add_u64 v[190:191], v[188:189], 0, s[6:7]
	v_cvt_pk_bf16_f32 v164, v164, v165
	v_cvt_pk_bf16_f32 v165, v166, v167
	v_cvt_pk_bf16_f32 v167, v170, v171
	v_cvt_pk_bf16_f32 v170, v160, v161
	v_add_co_u32_e32 v160, vcc, s11, v190
	v_cvt_pk_bf16_f32 v166, v168, v169
	v_cvt_pk_bf16_f32 v168, v172, v173
	v_cvt_pk_bf16_f32 v169, v174, v175
	v_cvt_pk_bf16_f32 v171, v162, v163
	v_addc_co_u32_e32 v161, vcc, 0, v191, vcc
	ds_write_b64 v193, v[164:165]
	ds_write_b64 v193, v[166:167] offset:2304
	ds_write_b64 v193, v[168:169] offset:4608
	ds_write_b64 v194, v[170:171]
	global_store_dwordx4 v[160:161], v[164:167], off
	global_store_dwordx4 v[160:161], v[168:171], off offset:1024
	s_waitcnt lgkmcnt(0)
	s_barrier
	ds_read_b128 v[164:167], v195
	ds_read_b128 v[168:171], v195 offset:64
	s_waitcnt vmcnt(16)
	v_lshlrev_b32_e32 v160, 16, v12
	v_and_b32_e32 v161, 0xffff0000, v12
	v_lshlrev_b32_e32 v162, 16, v13
	v_and_b32_e32 v163, 0xffff0000, v13
	ds_read_b128 v[172:175], v195 offset:2368
	ds_read_b128 v[198:201], v195 offset:4672
	s_waitcnt lgkmcnt(3)
	v_mfma_f32_16x16x32_bf16 v[160:163], v[0:3], v[164:167], v[160:163]
	v_lshlrev_b32_e32 v164, 16, v14
	v_and_b32_e32 v165, 0xffff0000, v14
	v_lshlrev_b32_e32 v166, 16, v15
	s_waitcnt lgkmcnt(2)
	v_mfma_f32_16x16x32_bf16 v[160:163], v[4:7], v[168:171], v[160:163]
	ds_read_b128 v[168:171], v195 offset:2304
	v_and_b32_e32 v167, 0xffff0000, v15
	ds_read_b128 v[202:205], v196 offset:64
	s_cmpk_lt_u32 s34, 0x76
	s_waitcnt lgkmcnt(1)
	v_mfma_f32_16x16x32_bf16 v[164:167], v[0:3], v[168:171], v[164:167]
	v_lshlrev_b32_e32 v168, 16, v8
	v_and_b32_e32 v169, 0xffff0000, v8
	v_lshlrev_b32_e32 v170, 16, v9
	v_mfma_f32_16x16x32_bf16 v[164:167], v[4:7], v[172:175], v[164:167]
	ds_read_b128 v[172:175], v195 offset:4608
	v_and_b32_e32 v171, 0xffff0000, v9
	s_cselect_b64 s[8:9], -1, 0
	s_and_b64 vcc, exec, s[8:9]
	s_waitcnt lgkmcnt(0)
	v_mfma_f32_16x16x32_bf16 v[168:171], v[0:3], v[172:175], v[168:171]
	v_lshlrev_b32_e32 v172, 16, v10
	v_and_b32_e32 v173, 0xffff0000, v10
	v_lshlrev_b32_e32 v174, 16, v11
	v_mfma_f32_16x16x32_bf16 v[168:171], v[4:7], v[198:201], v[168:171]
	ds_read_b128 v[198:201], v196
	v_and_b32_e32 v175, 0xffff0000, v11
	s_waitcnt lgkmcnt(0)
	s_nop 0
	v_mfma_f32_16x16x32_bf16 v[172:175], v[0:3], v[198:201], v[172:175]
	v_mfma_f32_16x16x32_bf16 v[172:175], v[4:7], v[202:205], v[172:175]
	s_cbranch_vccz .LBB0_910
	s_add_i32 s0, s4, 0xffff7000
	s_lshl_b64 s[24:25], s[0:1], 1
	v_lshl_add_u64 v[4:5], v[176:177], 0, s[24:25]
	v_lshl_add_u64 v[12:13], v[178:179], 0, s[24:25]
	global_load_dwordx4 v[0:3], v[4:5], off
	s_nop 0
	global_load_dwordx4 v[4:7], v[4:5], off offset:64
	s_nop 0
	global_load_dwordx4 v[8:11], v[12:13], off offset:1024
	s_nop 0
	global_load_dwordx4 v[12:15], v[12:13], off
.LBB0_910:
	v_cvt_pk_bf16_f32 v160, v160, v161
	v_cvt_pk_bf16_f32 v161, v162, v163
	v_cvt_pk_bf16_f32 v162, v164, v165
	v_cvt_pk_bf16_f32 v164, v168, v169
	v_add_co_u32_e32 v168, vcc, s12, v190
	v_cvt_pk_bf16_f32 v163, v166, v167
	v_cvt_pk_bf16_f32 v165, v170, v171
	v_cvt_pk_bf16_f32 v166, v172, v173
	v_cvt_pk_bf16_f32 v167, v174, v175
	v_addc_co_u32_e32 v169, vcc, 0, v191, vcc
	ds_write_b64 v193, v[160:161] offset:9216
	ds_write_b64 v193, v[162:163] offset:11520
	ds_write_b64 v193, v[164:165] offset:13824
	ds_write_b64 v194, v[166:167] offset:9216
	global_store_dwordx4 v[168:169], v[160:163], off
	global_store_dwordx4 v[168:169], v[164:167], off offset:1024
	s_waitcnt lgkmcnt(0)
	s_barrier
	ds_read_b128 v[164:167], v195 offset:9216
	ds_read_b128 v[168:171], v195 offset:9280
	s_waitcnt vmcnt(16)
	v_lshlrev_b32_e32 v160, 16, v28
	v_and_b32_e32 v161, 0xffff0000, v28
	v_lshlrev_b32_e32 v162, 16, v29
	v_and_b32_e32 v163, 0xffff0000, v29
	ds_read_b128 v[172:175], v195 offset:11584
	ds_read_b128 v[198:201], v195 offset:13888
	s_waitcnt lgkmcnt(3)
	v_mfma_f32_16x16x32_bf16 v[160:163], v[16:19], v[164:167], v[160:163]
	v_lshlrev_b32_e32 v164, 16, v30
	v_and_b32_e32 v165, 0xffff0000, v30
	v_lshlrev_b32_e32 v166, 16, v31
	s_waitcnt lgkmcnt(2)
	v_mfma_f32_16x16x32_bf16 v[160:163], v[20:23], v[168:171], v[160:163]
	ds_read_b128 v[168:171], v195 offset:11520
	v_and_b32_e32 v167, 0xffff0000, v31
	ds_read_b128 v[202:205], v196 offset:9280
	s_andn2_b64 vcc, exec, s[8:9]
	s_waitcnt lgkmcnt(1)
	v_mfma_f32_16x16x32_bf16 v[164:167], v[16:19], v[168:171], v[164:167]
	v_lshlrev_b32_e32 v168, 16, v24
	v_and_b32_e32 v169, 0xffff0000, v24
	v_lshlrev_b32_e32 v170, 16, v25
	v_mfma_f32_16x16x32_bf16 v[164:167], v[20:23], v[172:175], v[164:167]
	ds_read_b128 v[172:175], v195 offset:13824
	v_and_b32_e32 v171, 0xffff0000, v25
	s_waitcnt lgkmcnt(0)
	s_nop 0
	v_mfma_f32_16x16x32_bf16 v[168:171], v[16:19], v[172:175], v[168:171]
	v_lshlrev_b32_e32 v172, 16, v26
	v_and_b32_e32 v173, 0xffff0000, v26
	v_lshlrev_b32_e32 v174, 16, v27
	v_mfma_f32_16x16x32_bf16 v[168:171], v[20:23], v[198:201], v[168:171]
	ds_read_b128 v[198:201], v196 offset:9216
	v_and_b32_e32 v175, 0xffff0000, v27
	s_waitcnt lgkmcnt(0)
	s_nop 0
	v_mfma_f32_16x16x32_bf16 v[172:175], v[16:19], v[198:201], v[172:175]
	v_mfma_f32_16x16x32_bf16 v[172:175], v[20:23], v[202:205], v[172:175]
	s_cbranch_vccnz .LBB0_912
	s_add_i32 s0, s4, 0xffff8000
	s_lshl_b64 s[8:9], s[0:1], 1
	v_lshl_add_u64 v[20:21], v[176:177], 0, s[8:9]
	v_lshl_add_u64 v[28:29], v[178:179], 0, s[8:9]
	global_load_dwordx4 v[16:19], v[20:21], off
	s_nop 0
	global_load_dwordx4 v[20:23], v[20:21], off offset:64
	s_nop 0
	global_load_dwordx4 v[24:27], v[28:29], off offset:1024
	s_nop 0
	global_load_dwordx4 v[28:31], v[28:29], off
.LBB0_912:
	v_cvt_pk_bf16_f32 v160, v160, v161
	v_cvt_pk_bf16_f32 v161, v162, v163
	v_cvt_pk_bf16_f32 v162, v164, v165
	v_cvt_pk_bf16_f32 v164, v168, v169
	v_add_co_u32_e32 v168, vcc, s13, v190
	v_cvt_pk_bf16_f32 v163, v166, v167
	v_cvt_pk_bf16_f32 v165, v170, v171
	v_cvt_pk_bf16_f32 v166, v172, v173
	v_cvt_pk_bf16_f32 v167, v174, v175
	v_addc_co_u32_e32 v169, vcc, 0, v191, vcc
	ds_write_b64 v193, v[160:161]
	ds_write_b64 v193, v[162:163] offset:2304
	ds_write_b64 v193, v[164:165] offset:4608
	ds_write_b64 v194, v[166:167]
	global_store_dwordx4 v[168:169], v[160:163], off
	global_store_dwordx4 v[168:169], v[164:167], off offset:1024
	s_waitcnt lgkmcnt(0)
	s_barrier
	ds_read_b128 v[164:167], v195
	ds_read_b128 v[168:171], v195 offset:64
	s_waitcnt vmcnt(16)
	v_lshlrev_b32_e32 v160, 16, v44
	v_and_b32_e32 v161, 0xffff0000, v44
	v_lshlrev_b32_e32 v162, 16, v45
	v_and_b32_e32 v163, 0xffff0000, v45
	ds_read_b128 v[172:175], v195 offset:2368
	ds_read_b128 v[198:201], v195 offset:4672
	s_waitcnt lgkmcnt(3)
	v_mfma_f32_16x16x32_bf16 v[160:163], v[32:35], v[164:167], v[160:163]
	v_lshlrev_b32_e32 v164, 16, v46
	v_and_b32_e32 v165, 0xffff0000, v46
	v_lshlrev_b32_e32 v166, 16, v47
	s_waitcnt lgkmcnt(2)
	v_mfma_f32_16x16x32_bf16 v[160:163], v[36:39], v[168:171], v[160:163]
	ds_read_b128 v[168:171], v195 offset:2304
	v_and_b32_e32 v167, 0xffff0000, v47
	ds_read_b128 v[202:205], v196 offset:64
	s_cmpk_gt_u32 s34, 0x73
	s_waitcnt lgkmcnt(1)
	v_mfma_f32_16x16x32_bf16 v[164:167], v[32:35], v[168:171], v[164:167]
	v_lshlrev_b32_e32 v168, 16, v40
	v_and_b32_e32 v169, 0xffff0000, v40
	v_lshlrev_b32_e32 v170, 16, v41
	v_mfma_f32_16x16x32_bf16 v[164:167], v[36:39], v[172:175], v[164:167]
	ds_read_b128 v[172:175], v195 offset:4608
	v_and_b32_e32 v171, 0xffff0000, v41
	s_waitcnt lgkmcnt(0)
	s_nop 0
	v_mfma_f32_16x16x32_bf16 v[168:171], v[32:35], v[172:175], v[168:171]
	v_lshlrev_b32_e32 v172, 16, v42
	v_and_b32_e32 v173, 0xffff0000, v42
	v_lshlrev_b32_e32 v174, 16, v43
	v_mfma_f32_16x16x32_bf16 v[168:171], v[36:39], v[198:201], v[168:171]
	ds_read_b128 v[198:201], v196
	v_and_b32_e32 v175, 0xffff0000, v43
	s_waitcnt lgkmcnt(0)
	s_nop 0
	v_mfma_f32_16x16x32_bf16 v[172:175], v[32:35], v[198:201], v[172:175]
	v_mfma_f32_16x16x32_bf16 v[172:175], v[36:39], v[202:205], v[172:175]
	s_cbranch_scc1 .LBB0_914
	s_add_i32 s0, s4, 0xffff9000
	s_lshl_b64 s[8:9], s[0:1], 1
	v_lshl_add_u64 v[36:37], v[176:177], 0, s[8:9]
	v_lshl_add_u64 v[44:45], v[178:179], 0, s[8:9]
	global_load_dwordx4 v[32:35], v[36:37], off
	s_nop 0
	global_load_dwordx4 v[36:39], v[36:37], off offset:64
	s_nop 0
	global_load_dwordx4 v[40:43], v[44:45], off offset:1024
	s_nop 0
	global_load_dwordx4 v[44:47], v[44:45], off
.LBB0_914:
	v_cvt_pk_bf16_f32 v160, v160, v161
	v_cvt_pk_bf16_f32 v161, v162, v163
	v_cvt_pk_bf16_f32 v162, v164, v165
	v_cvt_pk_bf16_f32 v164, v168, v169
	v_add_co_u32_e32 v168, vcc, s14, v190
	v_cvt_pk_bf16_f32 v163, v166, v167
	v_cvt_pk_bf16_f32 v165, v170, v171
	v_cvt_pk_bf16_f32 v166, v172, v173
	v_cvt_pk_bf16_f32 v167, v174, v175
	v_addc_co_u32_e32 v169, vcc, 0, v191, vcc
	ds_write_b64 v193, v[160:161] offset:9216
	ds_write_b64 v193, v[162:163] offset:11520
	ds_write_b64 v193, v[164:165] offset:13824
	ds_write_b64 v194, v[166:167] offset:9216
	global_store_dwordx4 v[168:169], v[160:163], off
	global_store_dwordx4 v[168:169], v[164:167], off offset:1024
	s_waitcnt lgkmcnt(0)
	s_barrier
	ds_read_b128 v[164:167], v195 offset:9216
	ds_read_b128 v[168:171], v195 offset:9280
	s_waitcnt vmcnt(16)
	v_lshlrev_b32_e32 v160, 16, v60
	v_and_b32_e32 v161, 0xffff0000, v60
	v_lshlrev_b32_e32 v162, 16, v61
	v_and_b32_e32 v163, 0xffff0000, v61
	ds_read_b128 v[172:175], v195 offset:11584
	ds_read_b128 v[198:201], v195 offset:13888
	s_waitcnt lgkmcnt(3)
	v_mfma_f32_16x16x32_bf16 v[160:163], v[48:51], v[164:167], v[160:163]
	v_lshlrev_b32_e32 v164, 16, v62
	v_and_b32_e32 v165, 0xffff0000, v62
	v_lshlrev_b32_e32 v166, 16, v63
	s_waitcnt lgkmcnt(2)
	v_mfma_f32_16x16x32_bf16 v[160:163], v[52:55], v[168:171], v[160:163]
	ds_read_b128 v[168:171], v195 offset:11520
	v_and_b32_e32 v167, 0xffff0000, v63
	ds_read_b128 v[202:205], v196 offset:9280
	s_cmpk_gt_u32 s34, 0x72
	s_waitcnt lgkmcnt(1)
	v_mfma_f32_16x16x32_bf16 v[164:167], v[48:51], v[168:171], v[164:167]
	v_lshlrev_b32_e32 v168, 16, v56
	v_and_b32_e32 v169, 0xffff0000, v56
	v_lshlrev_b32_e32 v170, 16, v57
	v_mfma_f32_16x16x32_bf16 v[164:167], v[52:55], v[172:175], v[164:167]
	ds_read_b128 v[172:175], v195 offset:13824
	v_and_b32_e32 v171, 0xffff0000, v57
	s_waitcnt lgkmcnt(0)
	s_nop 0
	v_mfma_f32_16x16x32_bf16 v[168:171], v[48:51], v[172:175], v[168:171]
	v_lshlrev_b32_e32 v172, 16, v58
	v_and_b32_e32 v173, 0xffff0000, v58
	v_lshlrev_b32_e32 v174, 16, v59
	v_mfma_f32_16x16x32_bf16 v[168:171], v[52:55], v[198:201], v[168:171]
	ds_read_b128 v[198:201], v196 offset:9216
	v_and_b32_e32 v175, 0xffff0000, v59
	s_waitcnt lgkmcnt(0)
	s_nop 0
	v_mfma_f32_16x16x32_bf16 v[172:175], v[48:51], v[198:201], v[172:175]
	v_mfma_f32_16x16x32_bf16 v[172:175], v[52:55], v[202:205], v[172:175]
	s_cbranch_scc1 .LBB0_916
	s_add_i32 s0, s4, 0xffffa000
	s_lshl_b64 s[8:9], s[0:1], 1
	v_lshl_add_u64 v[52:53], v[176:177], 0, s[8:9]
	v_lshl_add_u64 v[60:61], v[178:179], 0, s[8:9]
	global_load_dwordx4 v[48:51], v[52:53], off
	s_nop 0
	global_load_dwordx4 v[52:55], v[52:53], off offset:64
	s_nop 0
	global_load_dwordx4 v[56:59], v[60:61], off offset:1024
	s_nop 0
	global_load_dwordx4 v[60:63], v[60:61], off
.LBB0_916:
	v_cvt_pk_bf16_f32 v160, v160, v161
	v_cvt_pk_bf16_f32 v161, v162, v163
	v_cvt_pk_bf16_f32 v162, v164, v165
	v_cvt_pk_bf16_f32 v164, v168, v169
	v_add_co_u32_e32 v168, vcc, s15, v190
	v_cvt_pk_bf16_f32 v163, v166, v167
	v_cvt_pk_bf16_f32 v165, v170, v171
	v_cvt_pk_bf16_f32 v166, v172, v173
	v_cvt_pk_bf16_f32 v167, v174, v175
	v_addc_co_u32_e32 v169, vcc, 0, v191, vcc
	ds_write_b64 v193, v[160:161]
	ds_write_b64 v193, v[162:163] offset:2304
	ds_write_b64 v193, v[164:165] offset:4608
	ds_write_b64 v194, v[166:167]
	global_store_dwordx4 v[168:169], v[160:163], off
	global_store_dwordx4 v[168:169], v[164:167], off offset:1024
	s_waitcnt lgkmcnt(0)
	s_barrier
	ds_read_b128 v[164:167], v195
	ds_read_b128 v[168:171], v195 offset:64
	s_waitcnt vmcnt(16)
	v_lshlrev_b32_e32 v160, 16, v76
	v_and_b32_e32 v161, 0xffff0000, v76
	v_lshlrev_b32_e32 v162, 16, v77
	v_and_b32_e32 v163, 0xffff0000, v77
	ds_read_b128 v[172:175], v195 offset:2368
	ds_read_b128 v[198:201], v195 offset:4672
	s_waitcnt lgkmcnt(3)
	v_mfma_f32_16x16x32_bf16 v[160:163], v[64:67], v[164:167], v[160:163]
	v_lshlrev_b32_e32 v164, 16, v78
	v_and_b32_e32 v165, 0xffff0000, v78
	v_lshlrev_b32_e32 v166, 16, v79
	s_waitcnt lgkmcnt(2)
	v_mfma_f32_16x16x32_bf16 v[160:163], v[68:71], v[168:171], v[160:163]
	ds_read_b128 v[168:171], v195 offset:2304
	v_and_b32_e32 v167, 0xffff0000, v79
	ds_read_b128 v[202:205], v196 offset:64
	s_cmpk_gt_u32 s34, 0x71
	s_waitcnt lgkmcnt(1)
	v_mfma_f32_16x16x32_bf16 v[164:167], v[64:67], v[168:171], v[164:167]
	v_lshlrev_b32_e32 v168, 16, v72
	v_and_b32_e32 v169, 0xffff0000, v72
	v_lshlrev_b32_e32 v170, 16, v73
	v_mfma_f32_16x16x32_bf16 v[164:167], v[68:71], v[172:175], v[164:167]
	ds_read_b128 v[172:175], v195 offset:4608
	v_and_b32_e32 v171, 0xffff0000, v73
	s_waitcnt lgkmcnt(0)
	s_nop 0
	v_mfma_f32_16x16x32_bf16 v[168:171], v[64:67], v[172:175], v[168:171]
	v_lshlrev_b32_e32 v172, 16, v74
	v_and_b32_e32 v173, 0xffff0000, v74
	v_lshlrev_b32_e32 v174, 16, v75
	v_mfma_f32_16x16x32_bf16 v[168:171], v[68:71], v[198:201], v[168:171]
	ds_read_b128 v[198:201], v196
	v_and_b32_e32 v175, 0xffff0000, v75
	s_waitcnt lgkmcnt(0)
	s_nop 0
	v_mfma_f32_16x16x32_bf16 v[172:175], v[64:67], v[198:201], v[172:175]
	v_mfma_f32_16x16x32_bf16 v[172:175], v[68:71], v[202:205], v[172:175]
	s_cbranch_scc1 .LBB0_918
	s_add_i32 s0, s4, 0xffffb000
	s_lshl_b64 s[8:9], s[0:1], 1
	v_lshl_add_u64 v[68:69], v[176:177], 0, s[8:9]
	v_lshl_add_u64 v[76:77], v[178:179], 0, s[8:9]
	global_load_dwordx4 v[64:67], v[68:69], off
	s_nop 0
	global_load_dwordx4 v[68:71], v[68:69], off offset:64
	s_nop 0
	global_load_dwordx4 v[72:75], v[76:77], off offset:1024
	s_nop 0
	global_load_dwordx4 v[76:79], v[76:77], off
.LBB0_918:
	v_cvt_pk_bf16_f32 v160, v160, v161
	v_cvt_pk_bf16_f32 v161, v162, v163
	v_cvt_pk_bf16_f32 v162, v164, v165
	v_cvt_pk_bf16_f32 v164, v168, v169
	v_add_co_u32_e32 v168, vcc, s16, v190
	v_cvt_pk_bf16_f32 v163, v166, v167
	v_cvt_pk_bf16_f32 v165, v170, v171
	v_cvt_pk_bf16_f32 v166, v172, v173
	v_cvt_pk_bf16_f32 v167, v174, v175
	v_addc_co_u32_e32 v169, vcc, 0, v191, vcc
	ds_write_b64 v193, v[160:161] offset:9216
	ds_write_b64 v193, v[162:163] offset:11520
	ds_write_b64 v193, v[164:165] offset:13824
	ds_write_b64 v194, v[166:167] offset:9216
	global_store_dwordx4 v[168:169], v[160:163], off
	global_store_dwordx4 v[168:169], v[164:167], off offset:1024
	s_waitcnt lgkmcnt(0)
	s_barrier
	ds_read_b128 v[164:167], v195 offset:9216
	ds_read_b128 v[168:171], v195 offset:9280
	s_waitcnt vmcnt(16)
	v_lshlrev_b32_e32 v160, 16, v92
	v_and_b32_e32 v161, 0xffff0000, v92
	v_lshlrev_b32_e32 v162, 16, v93
	v_and_b32_e32 v163, 0xffff0000, v93
	ds_read_b128 v[172:175], v195 offset:11584
	ds_read_b128 v[198:201], v195 offset:13888
	s_waitcnt lgkmcnt(3)
	v_mfma_f32_16x16x32_bf16 v[160:163], v[80:83], v[164:167], v[160:163]
	v_lshlrev_b32_e32 v164, 16, v94
	v_and_b32_e32 v165, 0xffff0000, v94
	v_lshlrev_b32_e32 v166, 16, v95
	s_waitcnt lgkmcnt(2)
	v_mfma_f32_16x16x32_bf16 v[160:163], v[84:87], v[168:171], v[160:163]
	ds_read_b128 v[168:171], v195 offset:11520
	v_and_b32_e32 v167, 0xffff0000, v95
	ds_read_b128 v[202:205], v196 offset:9280
	s_cmpk_gt_u32 s34, 0x70
	s_waitcnt lgkmcnt(1)
	v_mfma_f32_16x16x32_bf16 v[164:167], v[80:83], v[168:171], v[164:167]
	v_lshlrev_b32_e32 v168, 16, v88
	v_and_b32_e32 v169, 0xffff0000, v88
	v_lshlrev_b32_e32 v170, 16, v89
	v_mfma_f32_16x16x32_bf16 v[164:167], v[84:87], v[172:175], v[164:167]
	ds_read_b128 v[172:175], v195 offset:13824
	v_and_b32_e32 v171, 0xffff0000, v89
	s_waitcnt lgkmcnt(0)
	s_nop 0
	v_mfma_f32_16x16x32_bf16 v[168:171], v[80:83], v[172:175], v[168:171]
	v_lshlrev_b32_e32 v172, 16, v90
	v_and_b32_e32 v173, 0xffff0000, v90
	v_lshlrev_b32_e32 v174, 16, v91
	v_mfma_f32_16x16x32_bf16 v[168:171], v[84:87], v[198:201], v[168:171]
	ds_read_b128 v[198:201], v196 offset:9216
	v_and_b32_e32 v175, 0xffff0000, v91
	s_waitcnt lgkmcnt(0)
	s_nop 0
	v_mfma_f32_16x16x32_bf16 v[172:175], v[80:83], v[198:201], v[172:175]
	v_mfma_f32_16x16x32_bf16 v[172:175], v[84:87], v[202:205], v[172:175]
	s_cbranch_scc1 .LBB0_920
	s_add_i32 s0, s4, 0xffffc000
	s_lshl_b64 s[8:9], s[0:1], 1
	v_lshl_add_u64 v[84:85], v[176:177], 0, s[8:9]
	v_lshl_add_u64 v[92:93], v[178:179], 0, s[8:9]
	global_load_dwordx4 v[80:83], v[84:85], off
	s_nop 0
	global_load_dwordx4 v[84:87], v[84:85], off offset:64
	s_nop 0
	global_load_dwordx4 v[88:91], v[92:93], off offset:1024
	s_nop 0
	global_load_dwordx4 v[92:95], v[92:93], off
.LBB0_920:
	v_cvt_pk_bf16_f32 v160, v160, v161
	v_cvt_pk_bf16_f32 v161, v162, v163
	v_cvt_pk_bf16_f32 v162, v164, v165
	v_cvt_pk_bf16_f32 v164, v168, v169
	v_add_co_u32_e32 v168, vcc, s17, v190
	v_cvt_pk_bf16_f32 v163, v166, v167
	v_cvt_pk_bf16_f32 v165, v170, v171
	v_cvt_pk_bf16_f32 v166, v172, v173
	v_cvt_pk_bf16_f32 v167, v174, v175
	v_addc_co_u32_e32 v169, vcc, 0, v191, vcc
	ds_write_b64 v193, v[160:161]
	ds_write_b64 v193, v[162:163] offset:2304
	ds_write_b64 v193, v[164:165] offset:4608
	ds_write_b64 v194, v[166:167]
	global_store_dwordx4 v[168:169], v[160:163], off
	global_store_dwordx4 v[168:169], v[164:167], off offset:1024
	s_waitcnt lgkmcnt(0)
	s_barrier
	ds_read_b128 v[164:167], v195
	ds_read_b128 v[168:171], v195 offset:64
	s_waitcnt vmcnt(16)
	v_lshlrev_b32_e32 v160, 16, v108
	v_and_b32_e32 v161, 0xffff0000, v108
	v_lshlrev_b32_e32 v162, 16, v109
	v_and_b32_e32 v163, 0xffff0000, v109
	ds_read_b128 v[172:175], v195 offset:2368
	ds_read_b128 v[198:201], v195 offset:4672
	s_waitcnt lgkmcnt(3)
	v_mfma_f32_16x16x32_bf16 v[160:163], v[96:99], v[164:167], v[160:163]
	v_lshlrev_b32_e32 v164, 16, v110
	v_and_b32_e32 v165, 0xffff0000, v110
	v_lshlrev_b32_e32 v166, 16, v111
	s_waitcnt lgkmcnt(2)
	v_mfma_f32_16x16x32_bf16 v[160:163], v[100:103], v[168:171], v[160:163]
	ds_read_b128 v[168:171], v195 offset:2304
	v_and_b32_e32 v167, 0xffff0000, v111
	ds_read_b128 v[202:205], v196 offset:64
	s_cmpk_gt_u32 s34, 0x6f
	s_waitcnt lgkmcnt(1)
	v_mfma_f32_16x16x32_bf16 v[164:167], v[96:99], v[168:171], v[164:167]
	v_lshlrev_b32_e32 v168, 16, v104
	v_and_b32_e32 v169, 0xffff0000, v104
	v_lshlrev_b32_e32 v170, 16, v105
	v_mfma_f32_16x16x32_bf16 v[164:167], v[100:103], v[172:175], v[164:167]
	ds_read_b128 v[172:175], v195 offset:4608
	v_and_b32_e32 v171, 0xffff0000, v105
	s_waitcnt lgkmcnt(0)
	s_nop 0
	v_mfma_f32_16x16x32_bf16 v[168:171], v[96:99], v[172:175], v[168:171]
	v_lshlrev_b32_e32 v172, 16, v106
	v_and_b32_e32 v173, 0xffff0000, v106
	v_lshlrev_b32_e32 v174, 16, v107
	v_mfma_f32_16x16x32_bf16 v[168:171], v[100:103], v[198:201], v[168:171]
	ds_read_b128 v[198:201], v196
	v_and_b32_e32 v175, 0xffff0000, v107
	s_waitcnt lgkmcnt(0)
	s_nop 0
	v_mfma_f32_16x16x32_bf16 v[172:175], v[96:99], v[198:201], v[172:175]
	v_mfma_f32_16x16x32_bf16 v[172:175], v[100:103], v[202:205], v[172:175]
	s_cbranch_scc1 .LBB0_922
	s_add_i32 s0, s4, 0xffffd000
	s_lshl_b64 s[8:9], s[0:1], 1
	v_lshl_add_u64 v[100:101], v[176:177], 0, s[8:9]
	v_lshl_add_u64 v[108:109], v[178:179], 0, s[8:9]
	global_load_dwordx4 v[96:99], v[100:101], off
	s_nop 0
	global_load_dwordx4 v[100:103], v[100:101], off offset:64
	s_nop 0
	global_load_dwordx4 v[104:107], v[108:109], off offset:1024
	s_nop 0
	global_load_dwordx4 v[108:111], v[108:109], off
.LBB0_922:
	v_cvt_pk_bf16_f32 v160, v160, v161
	v_cvt_pk_bf16_f32 v161, v162, v163
	v_cvt_pk_bf16_f32 v162, v164, v165
	v_cvt_pk_bf16_f32 v164, v168, v169
	v_add_co_u32_e32 v168, vcc, s29, v190
	v_cvt_pk_bf16_f32 v163, v166, v167
	v_cvt_pk_bf16_f32 v165, v170, v171
	v_cvt_pk_bf16_f32 v166, v172, v173
	v_cvt_pk_bf16_f32 v167, v174, v175
	v_addc_co_u32_e32 v169, vcc, 0, v191, vcc
	ds_write_b64 v193, v[160:161] offset:9216
	ds_write_b64 v193, v[162:163] offset:11520
	ds_write_b64 v193, v[164:165] offset:13824
	ds_write_b64 v194, v[166:167] offset:9216
	global_store_dwordx4 v[168:169], v[160:163], off
	global_store_dwordx4 v[168:169], v[164:167], off offset:1024
	s_waitcnt lgkmcnt(0)
	s_barrier
	ds_read_b128 v[164:167], v195 offset:9216
	ds_read_b128 v[168:171], v195 offset:9280
	s_waitcnt vmcnt(16)
	v_lshlrev_b32_e32 v160, 16, v124
	v_and_b32_e32 v161, 0xffff0000, v124
	v_lshlrev_b32_e32 v162, 16, v125
	v_and_b32_e32 v163, 0xffff0000, v125
	ds_read_b128 v[172:175], v195 offset:11584
	ds_read_b128 v[198:201], v195 offset:13888
	s_waitcnt lgkmcnt(3)
	v_mfma_f32_16x16x32_bf16 v[160:163], v[112:115], v[164:167], v[160:163]
	ds_read_b128 v[202:205], v196 offset:9280
	s_cmpk_gt_u32 s34, 0x6e
	s_waitcnt lgkmcnt(3)
	v_mfma_f32_16x16x32_bf16 v[164:167], v[116:119], v[168:171], v[160:163]
	ds_read_b128 v[168:171], v195 offset:11520
	s_nop 2
	v_lshlrev_b32_e32 v160, 16, v126
	v_and_b32_e32 v161, 0xffff0000, v126
	v_lshlrev_b32_e32 v162, 16, v127
	v_and_b32_e32 v163, 0xffff0000, v127
	s_waitcnt lgkmcnt(0)
	s_nop 0
	v_mfma_f32_16x16x32_bf16 v[160:163], v[112:115], v[168:171], v[160:163]
	v_mfma_f32_16x16x32_bf16 v[168:171], v[116:119], v[172:175], v[160:163]
	ds_read_b128 v[172:175], v195 offset:13824
	s_nop 5
	v_lshlrev_b32_e32 v160, 16, v120
	v_and_b32_e32 v161, 0xffff0000, v120
	v_lshlrev_b32_e32 v162, 16, v121
	v_and_b32_e32 v163, 0xffff0000, v121
	s_waitcnt lgkmcnt(0)
	s_nop 0
	v_mfma_f32_16x16x32_bf16 v[160:163], v[112:115], v[172:175], v[160:163]
	v_mfma_f32_16x16x32_bf16 v[172:175], v[116:119], v[198:201], v[160:163]
	ds_read_b128 v[198:201], v196 offset:9216
	s_nop 5
	v_lshlrev_b32_e32 v160, 16, v122
	v_and_b32_e32 v161, 0xffff0000, v122
	v_lshlrev_b32_e32 v162, 16, v123
	v_and_b32_e32 v163, 0xffff0000, v123
	s_waitcnt lgkmcnt(0)
	s_nop 0
	v_mfma_f32_16x16x32_bf16 v[160:163], v[112:115], v[198:201], v[160:163]
	v_mfma_f32_16x16x32_bf16 v[160:163], v[116:119], v[202:205], v[160:163]
	s_cbranch_scc1 .LBB0_924
	s_add_i32 s0, s4, 0xffffe000
	s_lshl_b64 s[8:9], s[0:1], 1
	v_lshl_add_u64 v[116:117], v[176:177], 0, s[8:9]
	v_lshl_add_u64 v[124:125], v[178:179], 0, s[8:9]
	global_load_dwordx4 v[112:115], v[116:117], off
	s_nop 0
	global_load_dwordx4 v[116:119], v[116:117], off offset:64
	s_nop 0
	global_load_dwordx4 v[120:123], v[124:125], off offset:1024
	s_nop 0
	global_load_dwordx4 v[124:127], v[124:125], off
.LBB0_924:
	s_cmpk_gt_u32 s34, 0x77
	s_cselect_b64 s[8:9], -1, 0
	s_and_b64 vcc, exec, s[8:9]
	s_cbranch_vccnz .LBB0_927
	s_add_i32 s0, s10, s6
	s_add_i32 s0, s0, 0x10000
	v_cvt_pk_bf16_f32 v164, v164, v165
	v_cvt_pk_bf16_f32 v165, v166, v167
	v_cvt_pk_bf16_f32 v166, v168, v169
	v_cvt_pk_bf16_f32 v167, v170, v171
	v_cvt_pk_bf16_f32 v168, v172, v173
	v_cvt_pk_bf16_f32 v169, v174, v175
	v_cvt_pk_bf16_f32 v170, v160, v161
	v_cvt_pk_bf16_f32 v171, v162, v163
	v_lshl_add_u64 v[160:161], v[186:187], 0, s[0:1]
	ds_write_b64 v193, v[164:165]
	ds_write_b64 v193, v[166:167] offset:2304
	ds_write_b64 v193, v[168:169] offset:4608
	ds_write_b64 v194, v[170:171]
	global_store_dwordx4 v[160:161], v[164:167], off
	global_store_dwordx4 v[160:161], v[168:171], off offset:1024
	s_waitcnt lgkmcnt(0)
	s_barrier
	ds_read_b128 v[164:167], v195
	ds_read_b128 v[168:171], v195 offset:64
	s_waitcnt vmcnt(22)
	v_lshlrev_b32_e32 v160, 16, v140
	v_and_b32_e32 v161, 0xffff0000, v140
	v_lshlrev_b32_e32 v162, 16, v141
	v_and_b32_e32 v163, 0xffff0000, v141
	ds_read_b128 v[172:175], v195 offset:2368
	ds_read_b128 v[198:201], v195 offset:4672
	s_waitcnt lgkmcnt(3)
	v_mfma_f32_16x16x32_bf16 v[160:163], v[128:131], v[164:167], v[160:163]
	s_cmpk_gt_u32 s34, 0x6d
	ds_read_b128 v[202:205], v196 offset:64
	s_waitcnt lgkmcnt(3)
	v_mfma_f32_16x16x32_bf16 v[164:167], v[132:135], v[168:171], v[160:163]
	ds_read_b128 v[168:171], v195 offset:2304
	s_nop 2
	v_lshlrev_b32_e32 v160, 16, v142
	v_and_b32_e32 v161, 0xffff0000, v142
	v_lshlrev_b32_e32 v162, 16, v143
	v_and_b32_e32 v163, 0xffff0000, v143
	s_waitcnt lgkmcnt(0)
	s_nop 0
	v_mfma_f32_16x16x32_bf16 v[160:163], v[128:131], v[168:171], v[160:163]
	v_mfma_f32_16x16x32_bf16 v[168:171], v[132:135], v[172:175], v[160:163]
	ds_read_b128 v[172:175], v195 offset:4608
	s_nop 5
	v_lshlrev_b32_e32 v160, 16, v136
	v_and_b32_e32 v161, 0xffff0000, v136
	v_lshlrev_b32_e32 v162, 16, v137
	v_and_b32_e32 v163, 0xffff0000, v137
	s_waitcnt lgkmcnt(0)
	s_nop 0
	v_mfma_f32_16x16x32_bf16 v[160:163], v[128:131], v[172:175], v[160:163]
	v_mfma_f32_16x16x32_bf16 v[172:175], v[132:135], v[198:201], v[160:163]
	ds_read_b128 v[198:201], v196
	s_nop 5
	v_lshlrev_b32_e32 v160, 16, v138
	v_and_b32_e32 v161, 0xffff0000, v138
	v_lshlrev_b32_e32 v162, 16, v139
	v_and_b32_e32 v163, 0xffff0000, v139
	s_waitcnt lgkmcnt(0)
	s_nop 0
	v_mfma_f32_16x16x32_bf16 v[160:163], v[128:131], v[198:201], v[160:163]
	v_mfma_f32_16x16x32_bf16 v[160:163], v[132:135], v[202:205], v[160:163]
	s_cbranch_scc1 .LBB0_927
	s_add_i32 s0, s4, 0xfffff000
	s_lshl_b64 s[24:25], s[0:1], 1
	v_lshl_add_u64 v[132:133], v[176:177], 0, s[24:25]
	v_lshl_add_u64 v[140:141], v[178:179], 0, s[24:25]
	global_load_dwordx4 v[128:131], v[132:133], off
	s_nop 0
	global_load_dwordx4 v[132:135], v[132:133], off offset:64
	s_nop 0
	global_load_dwordx4 v[136:139], v[140:141], off offset:1024
	s_nop 0
	global_load_dwordx4 v[140:143], v[140:141], off
.LBB0_927:
	s_cmpk_gt_u32 s34, 0x76
	s_cbranch_scc1 .LBB0_907
	s_add_i32 s0, s10, s6
	s_add_i32 s0, s0, 0x12000
	v_cvt_pk_bf16_f32 v164, v164, v165
	v_cvt_pk_bf16_f32 v165, v166, v167
	v_cvt_pk_bf16_f32 v166, v168, v169
	v_cvt_pk_bf16_f32 v167, v170, v171
	v_cvt_pk_bf16_f32 v168, v172, v173
	v_cvt_pk_bf16_f32 v169, v174, v175
	v_cvt_pk_bf16_f32 v170, v160, v161
	v_cvt_pk_bf16_f32 v171, v162, v163
	v_lshl_add_u64 v[160:161], v[186:187], 0, s[0:1]
	ds_write_b64 v193, v[164:165] offset:9216
	ds_write_b64 v193, v[166:167] offset:11520
	ds_write_b64 v193, v[168:169] offset:13824
	ds_write_b64 v194, v[170:171] offset:9216
	global_store_dwordx4 v[160:161], v[164:167], off
	global_store_dwordx4 v[160:161], v[168:171], off offset:1024
	s_waitcnt lgkmcnt(0)
	s_barrier
	ds_read_b128 v[164:167], v195 offset:9216
	ds_read_b128 v[168:171], v195 offset:9280
	s_waitcnt vmcnt(18)
	v_lshlrev_b32_e32 v160, 16, v156
	v_and_b32_e32 v161, 0xffff0000, v156
	v_lshlrev_b32_e32 v162, 16, v157
	v_and_b32_e32 v163, 0xffff0000, v157
	ds_read_b128 v[172:175], v195 offset:11584
	ds_read_b128 v[198:201], v195 offset:13888
	s_waitcnt lgkmcnt(3)
	v_mfma_f32_16x16x32_bf16 v[160:163], v[144:147], v[164:167], v[160:163]
	s_cmpk_gt_u32 s34, 0x6c
	ds_read_b128 v[202:205], v196 offset:9280
	s_waitcnt lgkmcnt(3)
	v_mfma_f32_16x16x32_bf16 v[164:167], v[148:151], v[168:171], v[160:163]
	ds_read_b128 v[168:171], v195 offset:11520
	s_nop 2
	v_lshlrev_b32_e32 v160, 16, v158
	v_and_b32_e32 v161, 0xffff0000, v158
	v_lshlrev_b32_e32 v162, 16, v159
	v_and_b32_e32 v163, 0xffff0000, v159
	s_waitcnt lgkmcnt(0)
	s_nop 0
	v_mfma_f32_16x16x32_bf16 v[160:163], v[144:147], v[168:171], v[160:163]
	v_mfma_f32_16x16x32_bf16 v[168:171], v[148:151], v[172:175], v[160:163]
	ds_read_b128 v[172:175], v195 offset:13824
	s_nop 5
	v_lshlrev_b32_e32 v160, 16, v152
	v_and_b32_e32 v161, 0xffff0000, v152
	v_lshlrev_b32_e32 v162, 16, v153
	v_and_b32_e32 v163, 0xffff0000, v153
	s_waitcnt lgkmcnt(0)
	s_nop 0
	v_mfma_f32_16x16x32_bf16 v[160:163], v[144:147], v[172:175], v[160:163]
	v_mfma_f32_16x16x32_bf16 v[172:175], v[148:151], v[198:201], v[160:163]
	ds_read_b128 v[198:201], v196 offset:9216
	s_nop 5
	v_lshlrev_b32_e32 v160, 16, v154
	v_and_b32_e32 v161, 0xffff0000, v154
	v_lshlrev_b32_e32 v162, 16, v155
	v_and_b32_e32 v163, 0xffff0000, v155
	s_waitcnt lgkmcnt(0)
	s_nop 0
	v_mfma_f32_16x16x32_bf16 v[160:163], v[144:147], v[198:201], v[160:163]
	v_mfma_f32_16x16x32_bf16 v[160:163], v[148:151], v[202:205], v[160:163]
	s_cbranch_scc1 .LBB0_907
	s_mov_b32 s5, s1
	s_lshl_b64 s[24:25], s[4:5], 1
	v_lshl_add_u64 v[148:149], v[176:177], 0, s[24:25]
	v_lshl_add_u64 v[156:157], v[178:179], 0, s[24:25]
	global_load_dwordx4 v[144:147], v[148:149], off
	s_nop 0
	global_load_dwordx4 v[148:151], v[148:149], off offset:64
	s_nop 0
	global_load_dwordx4 v[152:155], v[156:157], off offset:1024
	s_nop 0
	global_load_dwordx4 v[156:159], v[156:157], off
	s_branch .LBB0_907

.LBB0_992:
	s_andn2_b64 vcc, exec, s[0:1]
	s_cbranch_vccnz .LBB0_994
	v_mov_b32_e32 v10, v181
	s_add_i32 s8, s69, 0xffffff00
	v_ashrrev_i32_e32 v17, 6, v10
	v_lshrrev_b32_e32 v0, 2, v10
	v_and_b32_e32 v19, 12, v0
	v_lshlrev_b32_e32 v11, 10, v17
	v_and_b32_e32 v18, 15, v10
	v_lshl_or_b32 v4, v19, 6, v11
	v_or_b32_e32 v0, v4, v18
	v_ashrrev_i32_e32 v1, 31, v0
	s_lshl_b64 s[0:1], s[8:9], 14
	v_lshlrev_b64 v[32:33], 2, v[0:1]
	v_ashrrev_i32_e32 v1, 31, v4
	s_add_u32 s12, s58, s0
	v_lshlrev_b64 v[34:35], 2, v[0:1]
	v_or_b32_e32 v6, 16, v0
	v_mov_b32_e32 v7, v1
	v_or_b32_e32 v8, 32, v0
	v_or_b32_e32 v0, 48, v0
	s_addc_u32 s13, s59, s1
	v_lshlrev_b64 v[36:37], 2, v[6:7]
	v_mov_b32_e32 v9, v1
	v_lshlrev_b64 v[40:41], 2, v[0:1]
	v_lshl_add_u64 v[2:3], s[12:13], 0, v[32:33]
	v_lshl_add_u64 v[6:7], s[12:13], 0, v[36:37]
	v_lshlrev_b64 v[38:39], 2, v[8:9]
	v_lshl_add_u64 v[0:1], s[12:13], 0, v[40:41]
	s_add_i32 s8, s69, 0xf00
	s_barrier
	v_lshl_add_u64 v[4:5], s[12:13], 0, v[34:35]
	v_lshl_add_u64 v[8:9], s[12:13], 0, v[38:39]
	global_load_dword v20, v[2:3], off
	global_load_dword v21, v[4:5], off offset:256
	global_load_dword v22, v[4:5], off offset:512
	global_load_dword v23, v[4:5], off offset:768
	global_load_dword v26, v[4:5], off offset:64
	global_load_dword v27, v[6:7], off offset:256
	global_load_dword v28, v[4:5], off offset:128
	global_load_dword v29, v[4:5], off offset:192
	global_load_dword v30, v[6:7], off offset:512
	global_load_dword v31, v[6:7], off offset:768
	global_load_dword v42, v[8:9], off offset:256
	global_load_dword v43, v[8:9], off offset:512
	global_load_dword v44, v[8:9], off offset:768
	global_load_dword v45, v[0:1], off offset:256
	global_load_dword v46, v[0:1], off offset:512
	global_load_dword v47, v[0:1], off offset:768
	s_lshl_b64 s[12:13], s[8:9], 13
	v_lshlrev_b32_e32 v0, 6, v10
	s_add_u32 s14, s37, s12
	v_and_or_b32 v0, v0, s67, v11
	v_and_b32_e32 v16, 63, v10
	s_addc_u32 s15, s38, s13
	v_ashrrev_i32_e32 v1, 31, v0
	v_lshl_add_u64 v[4:5], v[0:1], 1, s[14:15]
	v_lshl_or_b32 v0, v16, 4, v11
	s_add_u32 s14, s39, s12
	v_ashrrev_i32_e32 v1, 31, v0
	s_addc_u32 s15, s42, s13
	v_lshlrev_b64 v[24:25], 1, v[0:1]
	v_lshl_or_b32 v52, v16, 3, v11
	v_lshlrev_b32_e32 v52, 1, v52
	v_mov_b32_e32 v53, 0
	v_lshl_add_u64 v[12:13], s[14:15], 0, v[52:53]
	global_load_dwordx4 v[0:3], v[12:13], off
	v_and_b32_e32 v72, 48, v10
	v_lshl_add_u64 v[8:9], v[4:5], 0, v[72:73]
	global_load_dwordx4 v[4:7], v[8:9], off
	s_nop 0
	global_load_dwordx4 v[8:11], v[8:9], off offset:64
	s_nop 0
	global_load_dwordx4 v[12:15], v[12:13], off offset:1024
	v_or_b32_e32 v16, 48, v16
	v_mul_u32_u24_e32 v18, 0x48, v18
	v_lshlrev_b32_e32 v19, 1, v19
	v_mul_u32_u24_e32 v16, 0x48, v16
	s_add_u32 s12, s43, s12
	v_lshlrev_b32_e32 v48, 1, v18
	v_lshl_or_b32 v17, v17, 5, v19
	v_lshlrev_b32_e32 v49, 1, v16
	s_addc_u32 s13, s46, s13
	v_add_u32_e32 v50, v17, v48
	v_add_u32_e32 v51, v17, v49
	v_lshl_add_u64 v[24:25], s[12:13], 0, v[24:25]
	s_add_u32 s0, s47, s0
	s_addc_u32 s1, s56, s1
	s_waitcnt vmcnt(18)
	v_cvt_pk_bf16_f32 v16, v20, v21
	s_waitcnt vmcnt(10)
	v_cvt_pk_bf16_f32 v19, v30, v31
	v_cvt_pk_bf16_f32 v17, v22, v23
	ds_write_b64 v50, v[16:17]
	v_cvt_pk_bf16_f32 v18, v26, v27
	s_waitcnt vmcnt(9)
	v_cvt_pk_bf16_f32 v20, v28, v42
	s_waitcnt vmcnt(7)
	v_cvt_pk_bf16_f32 v21, v43, v44
	s_waitcnt vmcnt(6)
	v_cvt_pk_bf16_f32 v22, v29, v45
	s_waitcnt vmcnt(4)
	v_cvt_pk_bf16_f32 v23, v46, v47
	v_add_u32_e32 v28, v48, v72
	ds_write_b64 v50, v[18:19] offset:2304
	ds_write_b64 v50, v[20:21] offset:4608
	ds_write_b64 v51, v[22:23]
	global_store_dwordx4 v[24:25], v[16:19], off
	global_store_dwordx4 v[24:25], v[20:23], off offset:16
	s_waitcnt lgkmcnt(0)
	s_barrier
	ds_read_b128 v[20:23], v28
	ds_read_b128 v[24:27], v28 offset:64
	s_waitcnt vmcnt(5)
	v_lshlrev_b32_e32 v16, 16, v0
	v_and_b32_e32 v17, 0xffff0000, v0
	v_lshlrev_b32_e32 v18, 16, v1
	v_and_b32_e32 v19, 0xffff0000, v1
	v_lshlrev_b32_e32 v0, 16, v2
	v_and_b32_e32 v1, 0xffff0000, v2
	s_waitcnt vmcnt(4) lgkmcnt(1)
	v_mfma_f32_16x16x32_bf16 v[16:19], v[4:7], v[20:23], v[16:19]
	ds_read_b128 v[20:23], v28 offset:2304
	v_lshlrev_b32_e32 v2, 16, v3
	v_and_b32_e32 v3, 0xffff0000, v3
	s_waitcnt vmcnt(3) lgkmcnt(1)
	v_mfma_f32_16x16x32_bf16 v[16:19], v[8:11], v[24:27], v[16:19]
	ds_read_b128 v[24:27], v28 offset:2368
	s_waitcnt lgkmcnt(1)
	v_mfma_f32_16x16x32_bf16 v[0:3], v[4:7], v[20:23], v[0:3]
	s_waitcnt vmcnt(2)
	v_lshlrev_b32_e32 v20, 16, v12
	v_and_b32_e32 v21, 0xffff0000, v12
	v_lshlrev_b32_e32 v22, 16, v13
	s_waitcnt lgkmcnt(0)
	v_mfma_f32_16x16x32_bf16 v[0:3], v[8:11], v[24:27], v[0:3]
	ds_read_b128 v[24:27], v28 offset:4608
	v_and_b32_e32 v23, 0xffff0000, v13
	ds_read_b128 v[28:31], v28 offset:4672
	v_lshlrev_b32_e32 v12, 16, v14
	s_waitcnt lgkmcnt(1)
	v_mfma_f32_16x16x32_bf16 v[20:23], v[4:7], v[24:27], v[20:23]
	v_and_b32_e32 v13, 0xffff0000, v14
	v_lshlrev_b32_e32 v14, 16, v15
	v_and_b32_e32 v15, 0xffff0000, v15
	s_waitcnt lgkmcnt(0)
	v_mfma_f32_16x16x32_bf16 v[20:23], v[8:11], v[28:31], v[20:23]
	v_add_u32_e32 v28, v49, v72
	ds_read_b128 v[24:27], v28
	ds_read_b128 v[28:31], v28 offset:64
	s_waitcnt lgkmcnt(1)
	v_mfma_f32_16x16x32_bf16 v[4:7], v[4:7], v[24:27], v[12:15]
	s_waitcnt lgkmcnt(0)
	v_mfma_f32_16x16x32_bf16 v[4:7], v[8:11], v[28:31], v[4:7]
	v_lshl_add_u64 v[8:9], s[0:1], 0, v[32:33]
	global_store_dword v[8:9], v16, off
	v_lshl_add_u64 v[8:9], s[0:1], 0, v[34:35]
	v_lshl_add_u64 v[10:11], s[0:1], 0, v[36:37]
	global_store_dword v[8:9], v17, off offset:256
	global_store_dword v[8:9], v18, off offset:512
	global_store_dword v[8:9], v19, off offset:768
	global_store_dword v[8:9], v0, off offset:64
	global_store_dword v[10:11], v1, off offset:256
	global_store_dword v[10:11], v2, off offset:512
	global_store_dword v[10:11], v3, off offset:768
	global_store_dword v[8:9], v20, off offset:128
	v_lshl_add_u64 v[0:1], s[0:1], 0, v[38:39]
	global_store_dword v[0:1], v21, off offset:256
	global_store_dword v[0:1], v22, off offset:512
	global_store_dword v[0:1], v23, off offset:768
	global_store_dword v[8:9], v4, off offset:192
	v_lshl_add_u64 v[0:1], s[0:1], 0, v[40:41]
	global_store_dword v[0:1], v5, off offset:256
	global_store_dword v[0:1], v6, off offset:512
	global_store_dword v[0:1], v7, off offset:768
